# hand-written weight transposes (prep_b): all tiles of a block loaded up front, LDS transpose, 16-byte stores
# speedup vs baseline: 1.0049x; 1.0049x over previous
.LBB0_107:
	s_mov_b32 s28, s22
	s_and_b32 s2, s42, 7
	s_cmp_lg_u32 s2, 0
	s_cbranch_scc1 .Lxp_vb
	s_and_b32 s2, s22, 7
	s_ashr_i32 s3, s42, 3
	s_mul_i32 s2, s3, s2
	s_ashr_i32 s3, s22, 3
	s_add_i32 s28, s2, s3
.Lxp_vb:
	v_mbcnt_hi_u32_b32 v0, -1, v210
	s_lshr_b32 s29, s70, 6
	v_lshlrev_b32_e32 v1, 2, v0
	s_mul_i32 s4, s29, 260
	v_add_u32_e32 v2, s4, v1
	v_lshrrev_b32_e32 v3, 3, v0
	s_lshl_b32 s4, s29, 3
	v_add_u32_e32 v3, s4, v3
	v_and_b32_e32 v8, 7, v0
	v_lshlrev_b32_e32 v4, 4, v8
	v_mul_u32_u24_e32 v5, 2080, v8
	v_lshl_add_u32 v5, v3, 2, v5
	v_mov_b32_e32 v6, 0
	s_waitcnt vmcnt(0) lgkmcnt(0)
	s_barrier
	s_load_dwordx2 s[8:9], s[0:1], 0x30
	s_sub_u32 s2, s28, 0
	s_and_b32 s2, s2, 255
	s_cmp_lt_u32 s2, 384
	s_cselect_b32 s3, 1, 0
	s_cselect_b32 s2, s2, 0
	s_lshr_b32 s16, s2, 4
	s_and_b32 s17, s2, 15
	s_lshl_b32 s4, s16, 6
	s_mov_b32 s5, s4
	s_cmp_lt_u32 s4, 1472
	s_cselect_b32 s5, s5, 0
	s_lshl_b32 s6, s17, 6
	s_add_u32 s6, s6, s29
	s_mul_i32 s6, s6, 1472
	s_add_u32 s6, s6, s5
	s_lshl_b32 s6, s6, 2
	s_waitcnt lgkmcnt(0)
	s_add_u32 s8, s8, s6
	s_addc_u32 s9, s9, 0
	global_load_dword v16, v1, s[8:9]
	s_add_u32 s8, s8, 47104
	s_addc_u32 s9, s9, 0
	global_load_dword v17, v1, s[8:9]
	s_add_u32 s8, s8, 47104
	s_addc_u32 s9, s9, 0
	global_load_dword v18, v1, s[8:9]
	s_add_u32 s8, s8, 47104
	s_addc_u32 s9, s9, 0
	global_load_dword v19, v1, s[8:9]
	s_add_u32 s8, s8, 47104
	s_addc_u32 s9, s9, 0
	global_load_dword v20, v1, s[8:9]
	s_add_u32 s8, s8, 47104
	s_addc_u32 s9, s9, 0
	global_load_dword v21, v1, s[8:9]
	s_add_u32 s8, s8, 47104
	s_addc_u32 s9, s9, 0
	global_load_dword v22, v1, s[8:9]
	s_add_u32 s8, s8, 47104
	s_addc_u32 s9, s9, 0
	global_load_dword v23, v1, s[8:9]
	s_load_dwordx2 s[8:9], s[0:1], 0x30
	s_sub_u32 s2, s28, 0
	s_and_b32 s2, s2, 255
	s_add_u32 s2, s2, 256
	s_cmp_lt_u32 s2, 384
	s_cselect_b32 s3, 1, 0
	s_cselect_b32 s2, s2, 0
	s_lshr_b32 s16, s2, 4
	s_and_b32 s17, s2, 15
	s_lshl_b32 s4, s16, 6
	s_mov_b32 s5, s4
	s_cmp_lt_u32 s4, 1472
	s_cselect_b32 s5, s5, 0
	s_lshl_b32 s6, s17, 6
	s_add_u32 s6, s6, s29
	s_mul_i32 s6, s6, 1472
	s_add_u32 s6, s6, s5
	s_lshl_b32 s6, s6, 2
	s_waitcnt lgkmcnt(0)
	s_add_u32 s8, s8, s6
	s_addc_u32 s9, s9, 0
	global_load_dword v24, v1, s[8:9]
	s_add_u32 s8, s8, 47104
	s_addc_u32 s9, s9, 0
	global_load_dword v25, v1, s[8:9]
	s_add_u32 s8, s8, 47104
	s_addc_u32 s9, s9, 0
	global_load_dword v26, v1, s[8:9]
	s_add_u32 s8, s8, 47104
	s_addc_u32 s9, s9, 0
	global_load_dword v27, v1, s[8:9]
	s_add_u32 s8, s8, 47104
	s_addc_u32 s9, s9, 0
	global_load_dword v28, v1, s[8:9]
	s_add_u32 s8, s8, 47104
	s_addc_u32 s9, s9, 0
	global_load_dword v29, v1, s[8:9]
	s_add_u32 s8, s8, 47104
	s_addc_u32 s9, s9, 0
	global_load_dword v30, v1, s[8:9]
	s_add_u32 s8, s8, 47104
	s_addc_u32 s9, s9, 0
	global_load_dword v31, v1, s[8:9]
	s_load_dwordx2 s[8:9], s[0:1], 0x48
	s_sub_u32 s2, s28, 128
	s_and_b32 s2, s2, 255
	s_cmp_lt_u32 s2, 96
	s_cselect_b32 s3, 1, 0
	s_cselect_b32 s2, s2, 0
	s_lshr_b32 s16, s2, 2
	s_and_b32 s17, s2, 3
	s_lshl_b32 s4, s16, 6
	s_mov_b32 s5, s4
	s_lshl_b32 s6, s17, 6
	s_add_u32 s6, s6, s29
	s_mul_i32 s6, s6, 1536
	s_add_u32 s6, s6, s5
	s_lshl_b32 s6, s6, 2
	s_waitcnt lgkmcnt(0)
	s_add_u32 s8, s8, s6
	s_addc_u32 s9, s9, 0
	global_load_dword v32, v1, s[8:9]
	s_add_u32 s8, s8, 49152
	s_addc_u32 s9, s9, 0
	global_load_dword v33, v1, s[8:9]
	s_add_u32 s8, s8, 49152
	s_addc_u32 s9, s9, 0
	global_load_dword v34, v1, s[8:9]
	s_add_u32 s8, s8, 49152
	s_addc_u32 s9, s9, 0
	global_load_dword v35, v1, s[8:9]
	s_add_u32 s8, s8, 49152
	s_addc_u32 s9, s9, 0
	global_load_dword v36, v1, s[8:9]
	s_add_u32 s8, s8, 49152
	s_addc_u32 s9, s9, 0
	global_load_dword v37, v1, s[8:9]
	s_add_u32 s8, s8, 49152
	s_addc_u32 s9, s9, 0
	global_load_dword v38, v1, s[8:9]
	s_add_u32 s8, s8, 49152
	s_addc_u32 s9, s9, 0
	global_load_dword v39, v1, s[8:9]
	s_load_dwordx2 s[8:9], s[0:1], 0x50
	s_sub_u32 s2, s28, 224
	s_and_b32 s2, s2, 255
	s_cmp_lt_u32 s2, 64
	s_cselect_b32 s3, 1, 0
	s_cselect_b32 s2, s2, 0
	s_lshr_b32 s16, s2, 1
	s_and_b32 s17, s2, 1
	s_lshl_b32 s4, s16, 6
	s_mov_b32 s5, s4
	s_lshl_b32 s6, s17, 6
	s_add_u32 s6, s6, s29
	s_mul_i32 s6, s6, 2048
	s_add_u32 s6, s6, s5
	s_lshl_b32 s6, s6, 2
	s_waitcnt lgkmcnt(0)
	s_add_u32 s8, s8, s6
	s_addc_u32 s9, s9, 0
	global_load_dword v40, v1, s[8:9]
	s_add_u32 s8, s8, 65536
	s_addc_u32 s9, s9, 0
	global_load_dword v41, v1, s[8:9]
	s_add_u32 s8, s8, 65536
	s_addc_u32 s9, s9, 0
	global_load_dword v42, v1, s[8:9]
	s_add_u32 s8, s8, 65536
	s_addc_u32 s9, s9, 0
	global_load_dword v43, v1, s[8:9]
	s_add_u32 s8, s8, 65536
	s_addc_u32 s9, s9, 0
	global_load_dword v44, v1, s[8:9]
	s_add_u32 s8, s8, 65536
	s_addc_u32 s9, s9, 0
	global_load_dword v45, v1, s[8:9]
	s_add_u32 s8, s8, 65536
	s_addc_u32 s9, s9, 0
	global_load_dword v46, v1, s[8:9]
	s_add_u32 s8, s8, 65536
	s_addc_u32 s9, s9, 0
	global_load_dword v47, v1, s[8:9]
	s_load_dwordx2 s[8:9], s[0:1], 0x58
	s_sub_u32 s2, s28, 32
	s_and_b32 s2, s2, 255
	s_cmp_lt_u32 s2, 256
	s_cselect_b32 s3, 1, 0
	s_cselect_b32 s2, s2, 0
	s_lshr_b32 s16, s2, 4
	s_and_b32 s17, s2, 15
	s_lshl_b32 s4, s16, 6
	s_mov_b32 s5, s4
	s_lshl_b32 s6, s17, 6
	s_add_u32 s6, s6, s29
	s_mul_i32 s6, s6, 1024
	s_add_u32 s6, s6, s5
	s_lshl_b32 s6, s6, 2
	s_waitcnt lgkmcnt(0)
	s_add_u32 s8, s8, s6
	s_addc_u32 s9, s9, 0
	global_load_dword v48, v1, s[8:9]
	s_add_u32 s8, s8, 32768
	s_addc_u32 s9, s9, 0
	global_load_dword v49, v1, s[8:9]
	s_add_u32 s8, s8, 32768
	s_addc_u32 s9, s9, 0
	global_load_dword v50, v1, s[8:9]
	s_add_u32 s8, s8, 32768
	s_addc_u32 s9, s9, 0
	global_load_dword v51, v1, s[8:9]
	s_add_u32 s8, s8, 32768
	s_addc_u32 s9, s9, 0
	global_load_dword v52, v1, s[8:9]
	s_add_u32 s8, s8, 32768
	s_addc_u32 s9, s9, 0
	global_load_dword v53, v1, s[8:9]
	s_add_u32 s8, s8, 32768
	s_addc_u32 s9, s9, 0
	global_load_dword v54, v1, s[8:9]
	s_add_u32 s8, s8, 32768
	s_addc_u32 s9, s9, 0
	global_load_dword v55, v1, s[8:9]
	s_load_dwordx2 s[8:9], s[0:1], 0x30
	s_sub_u32 s2, s28, 32
	s_and_b32 s2, s2, 255
	s_cmp_lt_u32 s2, 384
	s_cselect_b32 s3, 1, 0
	s_cselect_b32 s2, s2, 0
	s_lshr_b32 s16, s2, 4
	s_and_b32 s17, s2, 15
	s_lshl_b32 s4, s16, 6
	s_mov_b32 s5, s4
	s_cmp_lt_u32 s4, 1472
	s_cselect_b32 s5, s5, 0
	s_lshl_b32 s6, s17, 6
	s_add_u32 s6, s6, s29
	s_mul_i32 s6, s6, 1472
	s_add_u32 s6, s6, s5
	s_lshl_b32 s6, s6, 2
	s_waitcnt lgkmcnt(0)
	s_add_u32 s8, s8, 0x5c0000
	s_addc_u32 s9, s9, 0
	s_add_u32 s8, s8, s6
	s_addc_u32 s9, s9, 0
	global_load_dword v56, v1, s[8:9]
	s_add_u32 s8, s8, 47104
	s_addc_u32 s9, s9, 0
	global_load_dword v57, v1, s[8:9]
	s_add_u32 s8, s8, 47104
	s_addc_u32 s9, s9, 0
	global_load_dword v58, v1, s[8:9]
	s_add_u32 s8, s8, 47104
	s_addc_u32 s9, s9, 0
	global_load_dword v59, v1, s[8:9]
	s_add_u32 s8, s8, 47104
	s_addc_u32 s9, s9, 0
	global_load_dword v60, v1, s[8:9]
	s_add_u32 s8, s8, 47104
	s_addc_u32 s9, s9, 0
	global_load_dword v61, v1, s[8:9]
	s_add_u32 s8, s8, 47104
	s_addc_u32 s9, s9, 0
	global_load_dword v62, v1, s[8:9]
	s_add_u32 s8, s8, 47104
	s_addc_u32 s9, s9, 0
	global_load_dword v63, v1, s[8:9]
	s_load_dwordx2 s[8:9], s[0:1], 0x30
	s_sub_u32 s2, s28, 32
	s_and_b32 s2, s2, 255
	s_add_u32 s2, s2, 256
	s_cmp_lt_u32 s2, 384
	s_cselect_b32 s3, 1, 0
	s_cselect_b32 s2, s2, 0
	s_lshr_b32 s16, s2, 4
	s_and_b32 s17, s2, 15
	s_lshl_b32 s4, s16, 6
	s_mov_b32 s5, s4
	s_cmp_lt_u32 s4, 1472
	s_cselect_b32 s5, s5, 0
	s_lshl_b32 s6, s17, 6
	s_add_u32 s6, s6, s29
	s_mul_i32 s6, s6, 1472
	s_add_u32 s6, s6, s5
	s_lshl_b32 s6, s6, 2
	s_waitcnt lgkmcnt(0)
	s_add_u32 s8, s8, 0x5c0000
	s_addc_u32 s9, s9, 0
	s_add_u32 s8, s8, s6
	s_addc_u32 s9, s9, 0
	global_load_dword v64, v1, s[8:9]
	s_add_u32 s8, s8, 47104
	s_addc_u32 s9, s9, 0
	global_load_dword v65, v1, s[8:9]
	s_add_u32 s8, s8, 47104
	s_addc_u32 s9, s9, 0
	global_load_dword v66, v1, s[8:9]
	s_add_u32 s8, s8, 47104
	s_addc_u32 s9, s9, 0
	global_load_dword v67, v1, s[8:9]
	s_add_u32 s8, s8, 47104
	s_addc_u32 s9, s9, 0
	global_load_dword v68, v1, s[8:9]
	s_add_u32 s8, s8, 47104
	s_addc_u32 s9, s9, 0
	global_load_dword v69, v1, s[8:9]
	s_add_u32 s8, s8, 47104
	s_addc_u32 s9, s9, 0
	global_load_dword v70, v1, s[8:9]
	s_add_u32 s8, s8, 47104
	s_addc_u32 s9, s9, 0
	global_load_dword v71, v1, s[8:9]
	s_load_dwordx2 s[8:9], s[0:1], 0x48
	s_sub_u32 s2, s28, 160
	s_and_b32 s2, s2, 255
	s_cmp_lt_u32 s2, 96
	s_cselect_b32 s3, 1, 0
	s_cselect_b32 s2, s2, 0
	s_lshr_b32 s16, s2, 2
	s_and_b32 s17, s2, 3
	s_lshl_b32 s4, s16, 6
	s_mov_b32 s5, s4
	s_lshl_b32 s6, s17, 6
	s_add_u32 s6, s6, s29
	s_mul_i32 s6, s6, 1536
	s_add_u32 s6, s6, s5
	s_lshl_b32 s6, s6, 2
	s_waitcnt lgkmcnt(0)
	s_add_u32 s8, s8, 0x180000
	s_addc_u32 s9, s9, 0
	s_add_u32 s8, s8, s6
	s_addc_u32 s9, s9, 0
	global_load_dword v72, v1, s[8:9]
	s_add_u32 s8, s8, 49152
	s_addc_u32 s9, s9, 0
	global_load_dword v73, v1, s[8:9]
	s_add_u32 s8, s8, 49152
	s_addc_u32 s9, s9, 0
	global_load_dword v74, v1, s[8:9]
	s_add_u32 s8, s8, 49152
	s_addc_u32 s9, s9, 0
	global_load_dword v75, v1, s[8:9]
	s_add_u32 s8, s8, 49152
	s_addc_u32 s9, s9, 0
	global_load_dword v76, v1, s[8:9]
	s_add_u32 s8, s8, 49152
	s_addc_u32 s9, s9, 0
	global_load_dword v77, v1, s[8:9]
	s_add_u32 s8, s8, 49152
	s_addc_u32 s9, s9, 0
	global_load_dword v78, v1, s[8:9]
	s_add_u32 s8, s8, 49152
	s_addc_u32 s9, s9, 0
	global_load_dword v79, v1, s[8:9]
	s_load_dwordx2 s[8:9], s[0:1], 0x50
	s_sub_u32 s2, s28, 0
	s_and_b32 s2, s2, 255
	s_cmp_lt_u32 s2, 64
	s_cselect_b32 s3, 1, 0
	s_cselect_b32 s2, s2, 0
	s_lshr_b32 s16, s2, 1
	s_and_b32 s17, s2, 1
	s_lshl_b32 s4, s16, 6
	s_mov_b32 s5, s4
	s_lshl_b32 s6, s17, 6
	s_add_u32 s6, s6, s29
	s_mul_i32 s6, s6, 2048
	s_add_u32 s6, s6, s5
	s_lshl_b32 s6, s6, 2
	s_waitcnt lgkmcnt(0)
	s_add_u32 s8, s8, 0x100000
	s_addc_u32 s9, s9, 0
	s_add_u32 s8, s8, s6
	s_addc_u32 s9, s9, 0
	global_load_dword v80, v1, s[8:9]
	s_add_u32 s8, s8, 65536
	s_addc_u32 s9, s9, 0
	global_load_dword v81, v1, s[8:9]
	s_add_u32 s8, s8, 65536
	s_addc_u32 s9, s9, 0
	global_load_dword v82, v1, s[8:9]
	s_add_u32 s8, s8, 65536
	s_addc_u32 s9, s9, 0
	global_load_dword v83, v1, s[8:9]
	s_add_u32 s8, s8, 65536
	s_addc_u32 s9, s9, 0
	global_load_dword v84, v1, s[8:9]
	s_add_u32 s8, s8, 65536
	s_addc_u32 s9, s9, 0
	global_load_dword v85, v1, s[8:9]
	s_add_u32 s8, s8, 65536
	s_addc_u32 s9, s9, 0
	global_load_dword v86, v1, s[8:9]
	s_add_u32 s8, s8, 65536
	s_addc_u32 s9, s9, 0
	global_load_dword v87, v1, s[8:9]
	s_load_dwordx2 s[8:9], s[0:1], 0x58
	s_sub_u32 s2, s28, 64
	s_and_b32 s2, s2, 255
	s_cmp_lt_u32 s2, 256
	s_cselect_b32 s3, 1, 0
	s_cselect_b32 s2, s2, 0
	s_lshr_b32 s16, s2, 4
	s_and_b32 s17, s2, 15
	s_lshl_b32 s4, s16, 6
	s_mov_b32 s5, s4
	s_lshl_b32 s6, s17, 6
	s_add_u32 s6, s6, s29
	s_mul_i32 s6, s6, 1024
	s_add_u32 s6, s6, s5
	s_lshl_b32 s6, s6, 2
	s_waitcnt lgkmcnt(0)
	s_add_u32 s8, s8, 0x400000
	s_addc_u32 s9, s9, 0
	s_add_u32 s8, s8, s6
	s_addc_u32 s9, s9, 0
	global_load_dword v88, v1, s[8:9]
	s_add_u32 s8, s8, 32768
	s_addc_u32 s9, s9, 0
	global_load_dword v89, v1, s[8:9]
	s_add_u32 s8, s8, 32768
	s_addc_u32 s9, s9, 0
	global_load_dword v90, v1, s[8:9]
	s_add_u32 s8, s8, 32768
	s_addc_u32 s9, s9, 0
	global_load_dword v91, v1, s[8:9]
	s_add_u32 s8, s8, 32768
	s_addc_u32 s9, s9, 0
	global_load_dword v92, v1, s[8:9]
	s_add_u32 s8, s8, 32768
	s_addc_u32 s9, s9, 0
	global_load_dword v93, v1, s[8:9]
	s_add_u32 s8, s8, 32768
	s_addc_u32 s9, s9, 0
	global_load_dword v94, v1, s[8:9]
	s_add_u32 s8, s8, 32768
	s_addc_u32 s9, s9, 0
	global_load_dword v95, v1, s[8:9]
	s_load_dwordx2 s[8:9], s[0:1], 0x60
	s_sub_u32 s2, s28, 64
	s_and_b32 s2, s2, 255
	s_cmp_lt_u32 s2, 576
	s_cselect_b32 s3, 1, 0
	s_cselect_b32 s2, s2, 0
	s_lshr_b32 s16, s2, 4
	s_and_b32 s17, s2, 15
	s_lshl_b32 s4, s16, 6
	s_mov_b32 s5, s4
	s_lshl_b32 s6, s17, 6
	s_add_u32 s6, s6, s29
	s_mul_i32 s6, s6, 2304
	s_add_u32 s6, s6, s5
	s_lshl_b32 s6, s6, 2
	s_waitcnt lgkmcnt(0)
	s_add_u32 s8, s8, s6
	s_addc_u32 s9, s9, 0
	global_load_dword v96, v1, s[8:9]
	s_add_u32 s8, s8, 73728
	s_addc_u32 s9, s9, 0
	global_load_dword v97, v1, s[8:9]
	s_add_u32 s8, s8, 73728
	s_addc_u32 s9, s9, 0
	global_load_dword v98, v1, s[8:9]
	s_add_u32 s8, s8, 73728
	s_addc_u32 s9, s9, 0
	global_load_dword v99, v1, s[8:9]
	s_add_u32 s8, s8, 73728
	s_addc_u32 s9, s9, 0
	global_load_dword v100, v1, s[8:9]
	s_add_u32 s8, s8, 73728
	s_addc_u32 s9, s9, 0
	global_load_dword v101, v1, s[8:9]
	s_add_u32 s8, s8, 73728
	s_addc_u32 s9, s9, 0
	global_load_dword v102, v1, s[8:9]
	s_add_u32 s8, s8, 73728
	s_addc_u32 s9, s9, 0
	global_load_dword v103, v1, s[8:9]
	s_load_dwordx2 s[8:9], s[0:1], 0x60
	s_sub_u32 s2, s28, 64
	s_and_b32 s2, s2, 255
	s_add_u32 s2, s2, 256
	s_cmp_lt_u32 s2, 576
	s_cselect_b32 s3, 1, 0
	s_cselect_b32 s2, s2, 0
	s_lshr_b32 s16, s2, 4
	s_and_b32 s17, s2, 15
	s_lshl_b32 s4, s16, 6
	s_mov_b32 s5, s4
	s_lshl_b32 s6, s17, 6
	s_add_u32 s6, s6, s29
	s_mul_i32 s6, s6, 2304
	s_add_u32 s6, s6, s5
	s_lshl_b32 s6, s6, 2
	s_waitcnt lgkmcnt(0)
	s_add_u32 s8, s8, s6
	s_addc_u32 s9, s9, 0
	global_load_dword v104, v1, s[8:9]
	s_add_u32 s8, s8, 73728
	s_addc_u32 s9, s9, 0
	global_load_dword v105, v1, s[8:9]
	s_add_u32 s8, s8, 73728
	s_addc_u32 s9, s9, 0
	global_load_dword v106, v1, s[8:9]
	s_add_u32 s8, s8, 73728
	s_addc_u32 s9, s9, 0
	global_load_dword v107, v1, s[8:9]
	s_add_u32 s8, s8, 73728
	s_addc_u32 s9, s9, 0
	global_load_dword v108, v1, s[8:9]
	s_add_u32 s8, s8, 73728
	s_addc_u32 s9, s9, 0
	global_load_dword v109, v1, s[8:9]
	s_add_u32 s8, s8, 73728
	s_addc_u32 s9, s9, 0
	global_load_dword v110, v1, s[8:9]
	s_add_u32 s8, s8, 73728
	s_addc_u32 s9, s9, 0
	global_load_dword v111, v1, s[8:9]
	s_load_dwordx2 s[8:9], s[0:1], 0x60
	s_sub_u32 s2, s28, 64
	s_and_b32 s2, s2, 255
	s_add_u32 s2, s2, 512
	s_cmp_lt_u32 s2, 576
	s_cselect_b32 s3, 1, 0
	s_cselect_b32 s2, s2, 0
	s_lshr_b32 s16, s2, 4
	s_and_b32 s17, s2, 15
	s_lshl_b32 s4, s16, 6
	s_mov_b32 s5, s4
	s_lshl_b32 s6, s17, 6
	s_add_u32 s6, s6, s29
	s_mul_i32 s6, s6, 2304
	s_add_u32 s6, s6, s5
	s_lshl_b32 s6, s6, 2
	s_waitcnt lgkmcnt(0)
	s_add_u32 s8, s8, s6
	s_addc_u32 s9, s9, 0
	global_load_dword v112, v1, s[8:9]
	s_add_u32 s8, s8, 73728
	s_addc_u32 s9, s9, 0
	global_load_dword v113, v1, s[8:9]
	s_add_u32 s8, s8, 73728
	s_addc_u32 s9, s9, 0
	global_load_dword v114, v1, s[8:9]
	s_add_u32 s8, s8, 73728
	s_addc_u32 s9, s9, 0
	global_load_dword v115, v1, s[8:9]
	s_add_u32 s8, s8, 73728
	s_addc_u32 s9, s9, 0
	global_load_dword v116, v1, s[8:9]
	s_add_u32 s8, s8, 73728
	s_addc_u32 s9, s9, 0
	global_load_dword v117, v1, s[8:9]
	s_add_u32 s8, s8, 73728
	s_addc_u32 s9, s9, 0
	global_load_dword v118, v1, s[8:9]
	s_add_u32 s8, s8, 73728
	s_addc_u32 s9, s9, 0
	global_load_dword v119, v1, s[8:9]
	s_load_dwordx2 s[8:9], s[0:1], 0x70
	s_sub_u32 s2, s28, 128
	s_and_b32 s2, s2, 255
	s_cmp_lt_u32 s2, 256
	s_cselect_b32 s3, 1, 0
	s_cselect_b32 s2, s2, 0
	s_lshr_b32 s16, s2, 4
	s_and_b32 s17, s2, 15
	s_lshl_b32 s4, s16, 6
	s_mov_b32 s5, s4
	s_lshl_b32 s6, s17, 6
	s_add_u32 s6, s6, s29
	s_mul_i32 s6, s6, 1024
	s_add_u32 s6, s6, s5
	s_lshl_b32 s6, s6, 2
	s_waitcnt lgkmcnt(0)
	s_add_u32 s8, s8, s6
	s_addc_u32 s9, s9, 0
	global_load_dword v120, v1, s[8:9]
	s_add_u32 s8, s8, 32768
	s_addc_u32 s9, s9, 0
	global_load_dword v121, v1, s[8:9]
	s_add_u32 s8, s8, 32768
	s_addc_u32 s9, s9, 0
	global_load_dword v122, v1, s[8:9]
	s_add_u32 s8, s8, 32768
	s_addc_u32 s9, s9, 0
	global_load_dword v123, v1, s[8:9]
	s_add_u32 s8, s8, 32768
	s_addc_u32 s9, s9, 0
	global_load_dword v124, v1, s[8:9]
	s_add_u32 s8, s8, 32768
	s_addc_u32 s9, s9, 0
	global_load_dword v125, v1, s[8:9]
	s_add_u32 s8, s8, 32768
	s_addc_u32 s9, s9, 0
	global_load_dword v126, v1, s[8:9]
	s_add_u32 s8, s8, 32768
	s_addc_u32 s9, s9, 0
	global_load_dword v127, v1, s[8:9]
	s_load_dwordx2 s[8:9], s[0:1], 0x78
	s_sub_u32 s2, s28, 128
	s_and_b32 s2, s2, 255
	s_cmp_lt_u32 s2, 960
	s_cselect_b32 s3, 1, 0
	s_cselect_b32 s2, s2, 0
	s_lshr_b32 s16, s2, 4
	s_and_b32 s17, s2, 15
	s_lshl_b32 s4, s16, 6
	s_add_u32 s5, s4, 48
	s_cmp_lt_u32 s16, 40
	s_cselect_b32 s5, s4, s5
	s_sub_u32 s6, s4, 0x400
	s_cmp_lt_u32 s16, 56
	s_cselect_b32 s5, s5, s6
	s_cmp_lt_u32 s4, 3632
	s_cselect_b32 s5, s5, 0
	s_lshl_b32 s6, s17, 6
	s_add_u32 s6, s6, s29
	s_mul_i32 s6, s6, 3632
	s_add_u32 s6, s6, s5
	s_lshl_b32 s6, s6, 2
	s_waitcnt lgkmcnt(0)
	s_add_u32 s8, s8, s6
	s_addc_u32 s9, s9, 0
	global_load_dword v128, v1, s[8:9]
	s_add_u32 s8, s8, 116224
	s_addc_u32 s9, s9, 0
	global_load_dword v129, v1, s[8:9]
	s_add_u32 s8, s8, 116224
	s_addc_u32 s9, s9, 0
	global_load_dword v130, v1, s[8:9]
	s_add_u32 s8, s8, 116224
	s_addc_u32 s9, s9, 0
	global_load_dword v131, v1, s[8:9]
	s_add_u32 s8, s8, 116224
	s_addc_u32 s9, s9, 0
	global_load_dword v132, v1, s[8:9]
	s_add_u32 s8, s8, 116224
	s_addc_u32 s9, s9, 0
	global_load_dword v133, v1, s[8:9]
	s_add_u32 s8, s8, 116224
	s_addc_u32 s9, s9, 0
	global_load_dword v134, v1, s[8:9]
	s_add_u32 s8, s8, 116224
	s_addc_u32 s9, s9, 0
	global_load_dword v135, v1, s[8:9]
	s_load_dwordx2 s[8:9], s[0:1], 0x78
	s_sub_u32 s2, s28, 128
	s_and_b32 s2, s2, 255
	s_add_u32 s2, s2, 256
	s_cmp_lt_u32 s2, 960
	s_cselect_b32 s3, 1, 0
	s_cselect_b32 s2, s2, 0
	s_lshr_b32 s16, s2, 4
	s_and_b32 s17, s2, 15
	s_lshl_b32 s4, s16, 6
	s_add_u32 s5, s4, 48
	s_cmp_lt_u32 s16, 40
	s_cselect_b32 s5, s4, s5
	s_sub_u32 s6, s4, 0x400
	s_cmp_lt_u32 s16, 56
	s_cselect_b32 s5, s5, s6
	s_cmp_lt_u32 s4, 3632
	s_cselect_b32 s5, s5, 0
	s_lshl_b32 s6, s17, 6
	s_add_u32 s6, s6, s29
	s_mul_i32 s6, s6, 3632
	s_add_u32 s6, s6, s5
	s_lshl_b32 s6, s6, 2
	s_waitcnt lgkmcnt(0)
	s_add_u32 s8, s8, s6
	s_addc_u32 s9, s9, 0
	global_load_dword v136, v1, s[8:9]
	s_add_u32 s8, s8, 116224
	s_addc_u32 s9, s9, 0
	global_load_dword v137, v1, s[8:9]
	s_add_u32 s8, s8, 116224
	s_addc_u32 s9, s9, 0
	global_load_dword v138, v1, s[8:9]
	s_add_u32 s8, s8, 116224
	s_addc_u32 s9, s9, 0
	global_load_dword v139, v1, s[8:9]
	s_add_u32 s8, s8, 116224
	s_addc_u32 s9, s9, 0
	global_load_dword v140, v1, s[8:9]
	s_add_u32 s8, s8, 116224
	s_addc_u32 s9, s9, 0
	global_load_dword v141, v1, s[8:9]
	s_add_u32 s8, s8, 116224
	s_addc_u32 s9, s9, 0
	global_load_dword v142, v1, s[8:9]
	s_add_u32 s8, s8, 116224
	s_addc_u32 s9, s9, 0
	global_load_dword v143, v1, s[8:9]
	s_load_dwordx2 s[8:9], s[0:1], 0x78
	s_sub_u32 s2, s28, 128
	s_and_b32 s2, s2, 255
	s_add_u32 s2, s2, 512
	s_cmp_lt_u32 s2, 960
	s_cselect_b32 s3, 1, 0
	s_cselect_b32 s2, s2, 0
	s_lshr_b32 s16, s2, 4
	s_and_b32 s17, s2, 15
	s_lshl_b32 s4, s16, 6
	s_add_u32 s5, s4, 48
	s_cmp_lt_u32 s16, 40
	s_cselect_b32 s5, s4, s5
	s_sub_u32 s6, s4, 0x400
	s_cmp_lt_u32 s16, 56
	s_cselect_b32 s5, s5, s6
	s_cmp_lt_u32 s4, 3632
	s_cselect_b32 s5, s5, 0
	s_lshl_b32 s6, s17, 6
	s_add_u32 s6, s6, s29
	s_mul_i32 s6, s6, 3632
	s_add_u32 s6, s6, s5
	s_lshl_b32 s6, s6, 2
	s_waitcnt lgkmcnt(0)
	s_add_u32 s8, s8, s6
	s_addc_u32 s9, s9, 0
	global_load_dword v144, v1, s[8:9]
	s_add_u32 s8, s8, 116224
	s_addc_u32 s9, s9, 0
	global_load_dword v145, v1, s[8:9]
	s_add_u32 s8, s8, 116224
	s_addc_u32 s9, s9, 0
	global_load_dword v146, v1, s[8:9]
	s_add_u32 s8, s8, 116224
	s_addc_u32 s9, s9, 0
	global_load_dword v147, v1, s[8:9]
	s_add_u32 s8, s8, 116224
	s_addc_u32 s9, s9, 0
	global_load_dword v148, v1, s[8:9]
	s_add_u32 s8, s8, 116224
	s_addc_u32 s9, s9, 0
	global_load_dword v149, v1, s[8:9]
	s_add_u32 s8, s8, 116224
	s_addc_u32 s9, s9, 0
	global_load_dword v150, v1, s[8:9]
	s_add_u32 s8, s8, 116224
	s_addc_u32 s9, s9, 0
	global_load_dword v151, v1, s[8:9]
	s_load_dwordx2 s[8:9], s[0:1], 0x78
	s_sub_u32 s2, s28, 128
	s_and_b32 s2, s2, 255
	s_add_u32 s2, s2, 768
	s_cmp_lt_u32 s2, 960
	s_cselect_b32 s3, 1, 0
	s_cselect_b32 s2, s2, 0
	s_lshr_b32 s16, s2, 4
	s_and_b32 s17, s2, 15
	s_lshl_b32 s4, s16, 6
	s_add_u32 s5, s4, 48
	s_cmp_lt_u32 s16, 40
	s_cselect_b32 s5, s4, s5
	s_sub_u32 s6, s4, 0x400
	s_cmp_lt_u32 s16, 56
	s_cselect_b32 s5, s5, s6
	s_cmp_lt_u32 s4, 3632
	s_cselect_b32 s5, s5, 0
	s_lshl_b32 s6, s17, 6
	s_add_u32 s6, s6, s29
	s_mul_i32 s6, s6, 3632
	s_add_u32 s6, s6, s5
	s_lshl_b32 s6, s6, 2
	s_waitcnt lgkmcnt(0)
	s_add_u32 s8, s8, s6
	s_addc_u32 s9, s9, 0
	global_load_dword v152, v1, s[8:9]
	s_add_u32 s8, s8, 116224
	s_addc_u32 s9, s9, 0
	global_load_dword v153, v1, s[8:9]
	s_add_u32 s8, s8, 116224
	s_addc_u32 s9, s9, 0
	global_load_dword v154, v1, s[8:9]
	s_add_u32 s8, s8, 116224
	s_addc_u32 s9, s9, 0
	global_load_dword v155, v1, s[8:9]
	s_add_u32 s8, s8, 116224
	s_addc_u32 s9, s9, 0
	global_load_dword v156, v1, s[8:9]
	s_add_u32 s8, s8, 116224
	s_addc_u32 s9, s9, 0
	global_load_dword v157, v1, s[8:9]
	s_add_u32 s8, s8, 116224
	s_addc_u32 s9, s9, 0
	global_load_dword v158, v1, s[8:9]
	s_add_u32 s8, s8, 116224
	s_addc_u32 s9, s9, 0
	global_load_dword v159, v1, s[8:9]
	s_load_dwordx2 s[8:9], s[0:1], 0x88
	s_sub_u32 s2, s28, 64
	s_and_b32 s2, s2, 255
	s_cmp_lt_u32 s2, 128
	s_cselect_b32 s3, 1, 0
	s_cselect_b32 s2, s2, 0
	s_lshr_b32 s16, s2, 5
	s_and_b32 s17, s2, 31
	s_lshl_b32 s4, s16, 6
	s_mov_b32 s5, s4
	s_cmp_lt_u32 s4, 128
	s_cselect_b32 s5, s5, 0
	s_lshl_b32 s6, s17, 6
	s_add_u32 s6, s6, s29
	s_mul_i32 s6, s6, 128
	s_add_u32 s6, s6, s5
	s_lshl_b32 s6, s6, 2
	s_waitcnt lgkmcnt(0)
	s_add_u32 s8, s8, s6
	s_addc_u32 s9, s9, 0
	global_load_dword v160, v1, s[8:9]
	s_add_u32 s8, s8, 4096
	s_addc_u32 s9, s9, 0
	global_load_dword v161, v1, s[8:9]
	s_add_u32 s8, s8, 4096
	s_addc_u32 s9, s9, 0
	global_load_dword v162, v1, s[8:9]
	s_add_u32 s8, s8, 4096
	s_addc_u32 s9, s9, 0
	global_load_dword v163, v1, s[8:9]
	s_add_u32 s8, s8, 4096
	s_addc_u32 s9, s9, 0
	global_load_dword v164, v1, s[8:9]
	s_add_u32 s8, s8, 4096
	s_addc_u32 s9, s9, 0
	global_load_dword v165, v1, s[8:9]
	s_add_u32 s8, s8, 4096
	s_addc_u32 s9, s9, 0
	global_load_dword v166, v1, s[8:9]
	s_add_u32 s8, s8, 4096
	s_addc_u32 s9, s9, 0
	global_load_dword v167, v1, s[8:9]
	s_load_dwordx2 s[8:9], s[0:1], 0x90
	s_sub_u32 s2, s28, 192
	s_and_b32 s2, s2, 255
	s_cmp_lt_u32 s2, 8
	s_cselect_b32 s3, 1, 0
	s_cselect_b32 s2, s2, 0
	s_lshr_b32 s16, s2, 1
	s_and_b32 s17, s2, 1
	s_lshl_b32 s4, s16, 6
	s_mov_b32 s5, s4
	s_cmp_lt_u32 s4, 64
	s_cselect_b32 s5, s5, 0
	s_lshl_b32 s6, s17, 6
	s_add_u32 s6, s6, s29
	s_mul_i32 s6, s6, 64
	s_add_u32 s6, s6, s5
	s_lshl_b32 s6, s6, 2
	s_waitcnt lgkmcnt(0)
	s_add_u32 s8, s8, s6
	s_addc_u32 s9, s9, 0
	global_load_dword v168, v1, s[8:9]
	s_add_u32 s8, s8, 2048
	s_addc_u32 s9, s9, 0
	global_load_dword v169, v1, s[8:9]
	s_add_u32 s8, s8, 2048
	s_addc_u32 s9, s9, 0
	global_load_dword v170, v1, s[8:9]
	s_add_u32 s8, s8, 2048
	s_addc_u32 s9, s9, 0
	global_load_dword v171, v1, s[8:9]
	s_add_u32 s8, s8, 2048
	s_addc_u32 s9, s9, 0
	global_load_dword v172, v1, s[8:9]
	s_add_u32 s8, s8, 2048
	s_addc_u32 s9, s9, 0
	global_load_dword v173, v1, s[8:9]
	s_add_u32 s8, s8, 2048
	s_addc_u32 s9, s9, 0
	global_load_dword v174, v1, s[8:9]
	s_add_u32 s8, s8, 2048
	s_addc_u32 s9, s9, 0
	global_load_dword v175, v1, s[8:9]
	s_load_dwordx2 s[8:9], s[0:1], 0x98
	s_sub_u32 s2, s28, 200
	s_and_b32 s2, s2, 255
	s_cmp_lt_u32 s2, 128
	s_cselect_b32 s3, 1, 0
	s_cselect_b32 s2, s2, 0
	s_lshr_b32 s16, s2, 5
	s_and_b32 s17, s2, 31
	s_lshl_b32 s4, s16, 6
	s_mov_b32 s5, s4
	s_cmp_lt_u32 s4, 128
	s_cselect_b32 s5, s5, 0
	s_lshl_b32 s6, s17, 6
	s_add_u32 s6, s6, s29
	s_mul_i32 s6, s6, 128
	s_add_u32 s6, s6, s5
	s_lshl_b32 s6, s6, 2
	s_waitcnt lgkmcnt(0)
	s_add_u32 s8, s8, s6
	s_addc_u32 s9, s9, 0
	global_load_dword v176, v1, s[8:9]
	s_add_u32 s8, s8, 4096
	s_addc_u32 s9, s9, 0
	global_load_dword v177, v1, s[8:9]
	s_add_u32 s8, s8, 4096
	s_addc_u32 s9, s9, 0
	global_load_dword v178, v1, s[8:9]
	s_add_u32 s8, s8, 4096
	s_addc_u32 s9, s9, 0
	global_load_dword v179, v1, s[8:9]
	s_add_u32 s8, s8, 4096
	s_addc_u32 s9, s9, 0
	global_load_dword v180, v1, s[8:9]
	s_add_u32 s8, s8, 4096
	s_addc_u32 s9, s9, 0
	global_load_dword v181, v1, s[8:9]
	s_add_u32 s8, s8, 4096
	s_addc_u32 s9, s9, 0
	global_load_dword v182, v1, s[8:9]
	s_add_u32 s8, s8, 4096
	s_addc_u32 s9, s9, 0
	global_load_dword v183, v1, s[8:9]
	s_load_dwordx2 s[8:9], s[0:1], 0xa0
	s_sub_u32 s2, s28, 72
	s_and_b32 s2, s2, 255
	s_cmp_lt_u32 s2, 8
	s_cselect_b32 s3, 1, 0
	s_cselect_b32 s2, s2, 0
	s_lshr_b32 s16, s2, 1
	s_and_b32 s17, s2, 1
	s_lshl_b32 s4, s16, 6
	s_mov_b32 s5, s4
	s_cmp_lt_u32 s4, 64
	s_cselect_b32 s5, s5, 0
	s_lshl_b32 s6, s17, 6
	s_add_u32 s6, s6, s29
	s_mul_i32 s6, s6, 64
	s_add_u32 s6, s6, s5
	s_lshl_b32 s6, s6, 2
	s_waitcnt lgkmcnt(0)
	s_add_u32 s8, s8, s6
	s_addc_u32 s9, s9, 0
	global_load_dword v184, v1, s[8:9]
	s_add_u32 s8, s8, 2048
	s_addc_u32 s9, s9, 0
	global_load_dword v185, v1, s[8:9]
	s_add_u32 s8, s8, 2048
	s_addc_u32 s9, s9, 0
	global_load_dword v186, v1, s[8:9]
	s_add_u32 s8, s8, 2048
	s_addc_u32 s9, s9, 0
	global_load_dword v187, v1, s[8:9]
	s_add_u32 s8, s8, 2048
	s_addc_u32 s9, s9, 0
	global_load_dword v188, v1, s[8:9]
	s_add_u32 s8, s8, 2048
	s_addc_u32 s9, s9, 0
	global_load_dword v189, v1, s[8:9]
	s_add_u32 s8, s8, 2048
	s_addc_u32 s9, s9, 0
	global_load_dword v190, v1, s[8:9]
	s_add_u32 s8, s8, 2048
	s_addc_u32 s9, s9, 0
	global_load_dword v191, v1, s[8:9]
	s_load_dwordx2 s[8:9], s[0:1], 0xa8
	s_sub_u32 s2, s28, 80
	s_and_b32 s2, s2, 255
	s_cmp_lt_u32 s2, 256
	s_cselect_b32 s3, 1, 0
	s_cselect_b32 s2, s2, 0
	s_lshr_b32 s16, s2, 4
	s_and_b32 s17, s2, 15
	s_lshl_b32 s4, s16, 6
	s_mov_b32 s5, s4
	s_lshl_b32 s6, s17, 6
	s_add_u32 s6, s6, s29
	s_mul_i32 s6, s6, 1024
	s_add_u32 s6, s6, s5
	s_lshl_b32 s6, s6, 2
	s_waitcnt lgkmcnt(0)
	s_add_u32 s8, s8, s6
	s_addc_u32 s9, s9, 0
	global_load_dword v192, v1, s[8:9]
	s_add_u32 s8, s8, 32768
	s_addc_u32 s9, s9, 0
	global_load_dword v193, v1, s[8:9]
	s_add_u32 s8, s8, 32768
	s_addc_u32 s9, s9, 0
	global_load_dword v194, v1, s[8:9]
	s_add_u32 s8, s8, 32768
	s_addc_u32 s9, s9, 0
	global_load_dword v195, v1, s[8:9]
	s_add_u32 s8, s8, 32768
	s_addc_u32 s9, s9, 0
	global_load_dword v196, v1, s[8:9]
	s_add_u32 s8, s8, 32768
	s_addc_u32 s9, s9, 0
	global_load_dword v197, v1, s[8:9]
	s_add_u32 s8, s8, 32768
	s_addc_u32 s9, s9, 0
	global_load_dword v198, v1, s[8:9]
	s_add_u32 s8, s8, 32768
	s_addc_u32 s9, s9, 0
	global_load_dword v199, v1, s[8:9]
	s_load_dwordx2 s[12:13], s[0:1], 0xc0
	s_sub_u32 s2, s28, 0
	s_and_b32 s2, s2, 255
	s_cmp_lt_u32 s2, 384
	s_cselect_b32 s3, 1, 0
	s_cselect_b32 s2, s2, 0
	s_lshr_b32 s16, s2, 4
	s_and_b32 s17, s2, 15
	s_waitcnt vmcnt(63) lgkmcnt(0)
	s_cmp_eq_u32 s3, 0
	s_cbranch_scc1 .Lxp_idle0
	s_lshl_b32 s4, s16, 6
	s_sub_u32 s4, 1472, s4
	s_max_i32 s4, s4, 0
	v_cmp_gt_u32_e32 vcc, s4, v0
	v_cndmask_b32_e32 v16, 0, v16, vcc
	v_cndmask_b32_e32 v17, 0, v17, vcc
	v_cndmask_b32_e32 v18, 0, v18, vcc
	v_cndmask_b32_e32 v19, 0, v19, vcc
	v_cndmask_b32_e32 v20, 0, v20, vcc
	v_cndmask_b32_e32 v21, 0, v21, vcc
	v_cndmask_b32_e32 v22, 0, v22, vcc
	v_cndmask_b32_e32 v23, 0, v23, vcc
	ds_write_b32 v2, v16 offset:0
	ds_write_b32 v2, v17 offset:2080
	ds_write_b32 v2, v18 offset:4160
	ds_write_b32 v2, v19 offset:6240
	ds_write_b32 v2, v20 offset:8320
	ds_write_b32 v2, v21 offset:10400
	ds_write_b32 v2, v22 offset:12480
	ds_write_b32 v2, v23 offset:14560
	s_waitcnt lgkmcnt(0)
	s_barrier
	ds_read_b32 v8, v5 offset:0
	ds_read_b32 v9, v5 offset:260
	ds_read_b32 v10, v5 offset:520
	ds_read_b32 v11, v5 offset:780
	ds_read_b32 v12, v5 offset:1040
	ds_read_b32 v13, v5 offset:1300
	ds_read_b32 v14, v5 offset:1560
	ds_read_b32 v15, v5 offset:1820
	s_lshl_b32 s4, s16, 17
	s_lshl_b32 s5, s17, 7
	s_add_u32 s4, s4, s5
	s_add_u32 s12, s12, s4
	s_addc_u32 s13, s13, 0
	v_lshl_add_u32 v7, v3, 11, v4
	s_waitcnt lgkmcnt(0)
	v_cvt_pk_bf16_f32 v224, v8, v9
	v_cvt_pk_bf16_f32 v225, v10, v11
	v_cvt_pk_bf16_f32 v226, v12, v13
	v_cvt_pk_bf16_f32 v227, v14, v15
	global_store_dwordx4 v7, v[224:227], s[12:13]
	s_branch .Lxp_next0

.Lxp_next0:
	s_load_dwordx2 s[12:13], s[0:1], 0xc0
	s_sub_u32 s2, s28, 0
	s_and_b32 s2, s2, 255
	s_add_u32 s2, s2, 256
	s_cmp_lt_u32 s2, 384
	s_cselect_b32 s3, 1, 0
	s_cselect_b32 s2, s2, 0
	s_lshr_b32 s16, s2, 4
	s_and_b32 s17, s2, 15
	s_waitcnt vmcnt(63) lgkmcnt(0)
	s_cmp_eq_u32 s3, 0
	s_cbranch_scc1 .Lxp_idle1
	s_lshl_b32 s4, s16, 6
	s_sub_u32 s4, 1472, s4
	s_max_i32 s4, s4, 0
	v_cmp_gt_u32_e32 vcc, s4, v0
	v_cndmask_b32_e32 v24, 0, v24, vcc
	v_cndmask_b32_e32 v25, 0, v25, vcc
	v_cndmask_b32_e32 v26, 0, v26, vcc
	v_cndmask_b32_e32 v27, 0, v27, vcc
	v_cndmask_b32_e32 v28, 0, v28, vcc
	v_cndmask_b32_e32 v29, 0, v29, vcc
	v_cndmask_b32_e32 v30, 0, v30, vcc
	v_cndmask_b32_e32 v31, 0, v31, vcc
	ds_write_b32 v2, v24 offset:16640
	ds_write_b32 v2, v25 offset:18720
	ds_write_b32 v2, v26 offset:20800
	ds_write_b32 v2, v27 offset:22880
	ds_write_b32 v2, v28 offset:24960
	ds_write_b32 v2, v29 offset:27040
	ds_write_b32 v2, v30 offset:29120
	ds_write_b32 v2, v31 offset:31200
	s_waitcnt lgkmcnt(0)
	s_barrier
	ds_read_b32 v8, v5 offset:16640
	ds_read_b32 v9, v5 offset:16900
	ds_read_b32 v10, v5 offset:17160
	ds_read_b32 v11, v5 offset:17420
	ds_read_b32 v12, v5 offset:17680
	ds_read_b32 v13, v5 offset:17940
	ds_read_b32 v14, v5 offset:18200
	ds_read_b32 v15, v5 offset:18460
	s_lshl_b32 s4, s16, 17
	s_lshl_b32 s5, s17, 7
	s_add_u32 s4, s4, s5
	s_add_u32 s12, s12, s4
	s_addc_u32 s13, s13, 0
	v_lshl_add_u32 v7, v3, 11, v4
	s_waitcnt lgkmcnt(0)
	v_cvt_pk_bf16_f32 v224, v8, v9
	v_cvt_pk_bf16_f32 v225, v10, v11
	v_cvt_pk_bf16_f32 v226, v12, v13
	v_cvt_pk_bf16_f32 v227, v14, v15
	global_store_dwordx4 v7, v[224:227], s[12:13]
	s_branch .Lxp_next1

.Lxp_next1:
	s_load_dwordx2 s[12:13], s[0:1], 0xd0
	s_load_dwordx2 s[14:15], s[0:1], 0x38
	s_sub_u32 s2, s28, 128
	s_and_b32 s2, s2, 255
	s_cmp_lt_u32 s2, 96
	s_cselect_b32 s3, 1, 0
	s_cselect_b32 s2, s2, 0
	s_lshr_b32 s16, s2, 2
	s_and_b32 s17, s2, 3
	s_waitcnt vmcnt(63) lgkmcnt(0)
	s_cmp_eq_u32 s3, 0
	s_cbranch_scc1 .Lxp_idle2
	s_lshl_b32 s4, s17, 6
	s_add_u32 s4, s4, s29
	s_lshl_b32 s4, s4, 2
	s_add_u32 s14, s14, s4
	s_addc_u32 s15, s15, 0
	global_load_dword v216, v6, s[14:15] offset:0
	global_load_dword v217, v6, s[14:15] offset:32
	global_load_dword v218, v6, s[14:15] offset:64
	global_load_dword v219, v6, s[14:15] offset:96
	global_load_dword v220, v6, s[14:15] offset:128
	global_load_dword v221, v6, s[14:15] offset:160
	global_load_dword v222, v6, s[14:15] offset:192
	global_load_dword v223, v6, s[14:15] offset:224
	s_waitcnt vmcnt(0)
	v_mul_f32_e32 v32, v32, v216
	v_mul_f32_e32 v33, v33, v217
	v_mul_f32_e32 v34, v34, v218
	v_mul_f32_e32 v35, v35, v219
	v_mul_f32_e32 v36, v36, v220
	v_mul_f32_e32 v37, v37, v221
	v_mul_f32_e32 v38, v38, v222
	v_mul_f32_e32 v39, v39, v223
	ds_write_b32 v2, v32 offset:0
	ds_write_b32 v2, v33 offset:2080
	ds_write_b32 v2, v34 offset:4160
	ds_write_b32 v2, v35 offset:6240
	ds_write_b32 v2, v36 offset:8320
	ds_write_b32 v2, v37 offset:10400
	ds_write_b32 v2, v38 offset:12480
	ds_write_b32 v2, v39 offset:14560
	s_waitcnt lgkmcnt(0)
	s_barrier
	ds_read_b32 v8, v5 offset:0
	ds_read_b32 v9, v5 offset:260
	ds_read_b32 v10, v5 offset:520
	ds_read_b32 v11, v5 offset:780
	ds_read_b32 v12, v5 offset:1040
	ds_read_b32 v13, v5 offset:1300
	ds_read_b32 v14, v5 offset:1560
	ds_read_b32 v15, v5 offset:1820
	s_lshl_b32 s4, s16, 15
	s_lshl_b32 s5, s17, 7
	s_add_u32 s4, s4, s5
	s_add_u32 s12, s12, s4
	s_addc_u32 s13, s13, 0
	v_lshl_add_u32 v7, v3, 9, v4
	s_waitcnt lgkmcnt(0)
	v_cvt_pk_bf16_f32 v224, v8, v9
	v_cvt_pk_bf16_f32 v225, v10, v11
	v_cvt_pk_bf16_f32 v226, v12, v13
	v_cvt_pk_bf16_f32 v227, v14, v15
	global_store_dwordx4 v7, v[224:227], s[12:13]
	s_branch .Lxp_next2

.Lxp_next2:
	s_load_dwordx2 s[12:13], s[0:1], 0xe0
	s_load_dwordx2 s[14:15], s[0:1], 0x40
	s_sub_u32 s2, s28, 224
	s_and_b32 s2, s2, 255
	s_cmp_lt_u32 s2, 64
	s_cselect_b32 s3, 1, 0
	s_cselect_b32 s2, s2, 0
	s_lshr_b32 s16, s2, 1
	s_and_b32 s17, s2, 1
	s_waitcnt vmcnt(63) lgkmcnt(0)
	s_cmp_eq_u32 s3, 0
	s_cbranch_scc1 .Lxp_idle3
	s_lshl_b32 s4, s17, 6
	s_add_u32 s4, s4, s29
	s_lshl_b32 s4, s4, 2
	s_add_u32 s14, s14, s4
	s_addc_u32 s15, s15, 0
	global_load_dword v216, v6, s[14:15] offset:0
	global_load_dword v217, v6, s[14:15] offset:32
	global_load_dword v218, v6, s[14:15] offset:64
	global_load_dword v219, v6, s[14:15] offset:96
	global_load_dword v220, v6, s[14:15] offset:128
	global_load_dword v221, v6, s[14:15] offset:160
	global_load_dword v222, v6, s[14:15] offset:192
	global_load_dword v223, v6, s[14:15] offset:224
	s_waitcnt vmcnt(0)
	v_mul_f32_e32 v40, v40, v216
	v_mul_f32_e32 v41, v41, v217
	v_mul_f32_e32 v42, v42, v218
	v_mul_f32_e32 v43, v43, v219
	v_mul_f32_e32 v44, v44, v220
	v_mul_f32_e32 v45, v45, v221
	v_mul_f32_e32 v46, v46, v222
	v_mul_f32_e32 v47, v47, v223
	ds_write_b32 v2, v40 offset:16640
	ds_write_b32 v2, v41 offset:18720
	ds_write_b32 v2, v42 offset:20800
	ds_write_b32 v2, v43 offset:22880
	ds_write_b32 v2, v44 offset:24960
	ds_write_b32 v2, v45 offset:27040
	ds_write_b32 v2, v46 offset:29120
	ds_write_b32 v2, v47 offset:31200
	s_waitcnt lgkmcnt(0)
	s_barrier
	ds_read_b32 v8, v5 offset:16640
	ds_read_b32 v9, v5 offset:16900
	ds_read_b32 v10, v5 offset:17160
	ds_read_b32 v11, v5 offset:17420
	ds_read_b32 v12, v5 offset:17680
	ds_read_b32 v13, v5 offset:17940
	ds_read_b32 v14, v5 offset:18200
	ds_read_b32 v15, v5 offset:18460
	s_lshl_b32 s4, s16, 14
	s_lshl_b32 s5, s17, 7
	s_add_u32 s4, s4, s5
	s_add_u32 s12, s12, s4
	s_addc_u32 s13, s13, 0
	v_lshl_add_u32 v7, v3, 8, v4
	s_waitcnt lgkmcnt(0)
	v_cvt_pk_bf16_f32 v224, v8, v9
	v_cvt_pk_bf16_f32 v225, v10, v11
	v_cvt_pk_bf16_f32 v226, v12, v13
	v_cvt_pk_bf16_f32 v227, v14, v15
	global_store_dwordx4 v7, v[224:227], s[12:13]
	s_branch .Lxp_next3

.Lxp_next3:
	s_load_dwordx2 s[12:13], s[0:1], 0xf0
	s_sub_u32 s2, s28, 32
	s_and_b32 s2, s2, 255
	s_cmp_lt_u32 s2, 256
	s_cselect_b32 s3, 1, 0
	s_cselect_b32 s2, s2, 0
	s_lshr_b32 s16, s2, 4
	s_and_b32 s17, s2, 15
	s_waitcnt vmcnt(63) lgkmcnt(0)
	s_cmp_eq_u32 s3, 0
	s_cbranch_scc1 .Lxp_idle4
	ds_write_b32 v2, v48 offset:0
	ds_write_b32 v2, v49 offset:2080
	ds_write_b32 v2, v50 offset:4160
	ds_write_b32 v2, v51 offset:6240
	ds_write_b32 v2, v52 offset:8320
	ds_write_b32 v2, v53 offset:10400
	ds_write_b32 v2, v54 offset:12480
	ds_write_b32 v2, v55 offset:14560
	s_waitcnt lgkmcnt(0)
	s_barrier
	ds_read_b32 v8, v5 offset:0
	ds_read_b32 v9, v5 offset:260
	ds_read_b32 v10, v5 offset:520
	ds_read_b32 v11, v5 offset:780
	ds_read_b32 v12, v5 offset:1040
	ds_read_b32 v13, v5 offset:1300
	ds_read_b32 v14, v5 offset:1560
	ds_read_b32 v15, v5 offset:1820
	s_lshl_b32 s4, s16, 17
	s_lshl_b32 s5, s17, 7
	s_add_u32 s4, s4, s5
	s_add_u32 s12, s12, s4
	s_addc_u32 s13, s13, 0
	v_lshl_add_u32 v7, v3, 11, v4
	s_waitcnt lgkmcnt(0)
	v_cvt_pk_bf16_f32 v224, v8, v9
	v_cvt_pk_bf16_f32 v225, v10, v11
	v_cvt_pk_bf16_f32 v226, v12, v13
	v_cvt_pk_bf16_f32 v227, v14, v15
	global_store_dwordx4 v7, v[224:227], s[12:13]
	s_branch .Lxp_next4

.Lxp_next4:
	s_load_dwordx2 s[12:13], s[0:1], 0xc8
	s_sub_u32 s2, s28, 32
	s_and_b32 s2, s2, 255
	s_cmp_lt_u32 s2, 384
	s_cselect_b32 s3, 1, 0
	s_cselect_b32 s2, s2, 0
	s_lshr_b32 s16, s2, 4
	s_and_b32 s17, s2, 15
	s_waitcnt vmcnt(63) lgkmcnt(0)
	s_cmp_eq_u32 s3, 0
	s_cbranch_scc1 .Lxp_idle5
	s_lshl_b32 s4, s16, 6
	s_sub_u32 s4, 1472, s4
	s_max_i32 s4, s4, 0
	v_cmp_gt_u32_e32 vcc, s4, v0
	v_cndmask_b32_e32 v56, 0, v56, vcc
	v_cndmask_b32_e32 v57, 0, v57, vcc
	v_cndmask_b32_e32 v58, 0, v58, vcc
	v_cndmask_b32_e32 v59, 0, v59, vcc
	v_cndmask_b32_e32 v60, 0, v60, vcc
	v_cndmask_b32_e32 v61, 0, v61, vcc
	v_cndmask_b32_e32 v62, 0, v62, vcc
	v_cndmask_b32_e32 v63, 0, v63, vcc
	ds_write_b32 v2, v56 offset:16640
	ds_write_b32 v2, v57 offset:18720
	ds_write_b32 v2, v58 offset:20800
	ds_write_b32 v2, v59 offset:22880
	ds_write_b32 v2, v60 offset:24960
	ds_write_b32 v2, v61 offset:27040
	ds_write_b32 v2, v62 offset:29120
	ds_write_b32 v2, v63 offset:31200
	s_waitcnt lgkmcnt(0)
	s_barrier
	ds_read_b32 v8, v5 offset:16640
	ds_read_b32 v9, v5 offset:16900
	ds_read_b32 v10, v5 offset:17160
	ds_read_b32 v11, v5 offset:17420
	ds_read_b32 v12, v5 offset:17680
	ds_read_b32 v13, v5 offset:17940
	ds_read_b32 v14, v5 offset:18200
	ds_read_b32 v15, v5 offset:18460
	s_lshl_b32 s4, s16, 17
	s_lshl_b32 s5, s17, 7
	s_add_u32 s4, s4, s5
	s_add_u32 s12, s12, s4
	s_addc_u32 s13, s13, 0
	v_lshl_add_u32 v7, v3, 11, v4
	s_waitcnt lgkmcnt(0)
	v_cvt_pk_bf16_f32 v224, v8, v9
	v_cvt_pk_bf16_f32 v225, v10, v11
	v_cvt_pk_bf16_f32 v226, v12, v13
	v_cvt_pk_bf16_f32 v227, v14, v15
	global_store_dwordx4 v7, v[224:227], s[12:13]
	s_branch .Lxp_next5

.Lxp_next5:
	s_load_dwordx2 s[12:13], s[0:1], 0xc8
	s_sub_u32 s2, s28, 32
	s_and_b32 s2, s2, 255
	s_add_u32 s2, s2, 256
	s_cmp_lt_u32 s2, 384
	s_cselect_b32 s3, 1, 0
	s_cselect_b32 s2, s2, 0
	s_lshr_b32 s16, s2, 4
	s_and_b32 s17, s2, 15
	s_waitcnt vmcnt(63) lgkmcnt(0)
	s_cmp_eq_u32 s3, 0
	s_cbranch_scc1 .Lxp_idle6
	s_lshl_b32 s4, s16, 6
	s_sub_u32 s4, 1472, s4
	s_max_i32 s4, s4, 0
	v_cmp_gt_u32_e32 vcc, s4, v0
	v_cndmask_b32_e32 v64, 0, v64, vcc
	v_cndmask_b32_e32 v65, 0, v65, vcc
	v_cndmask_b32_e32 v66, 0, v66, vcc
	v_cndmask_b32_e32 v67, 0, v67, vcc
	v_cndmask_b32_e32 v68, 0, v68, vcc
	v_cndmask_b32_e32 v69, 0, v69, vcc
	v_cndmask_b32_e32 v70, 0, v70, vcc
	v_cndmask_b32_e32 v71, 0, v71, vcc
	ds_write_b32 v2, v64 offset:0
	ds_write_b32 v2, v65 offset:2080
	ds_write_b32 v2, v66 offset:4160
	ds_write_b32 v2, v67 offset:6240
	ds_write_b32 v2, v68 offset:8320
	ds_write_b32 v2, v69 offset:10400
	ds_write_b32 v2, v70 offset:12480
	ds_write_b32 v2, v71 offset:14560
	s_waitcnt lgkmcnt(0)
	s_barrier
	ds_read_b32 v8, v5 offset:0
	ds_read_b32 v9, v5 offset:260
	ds_read_b32 v10, v5 offset:520
	ds_read_b32 v11, v5 offset:780
	ds_read_b32 v12, v5 offset:1040
	ds_read_b32 v13, v5 offset:1300
	ds_read_b32 v14, v5 offset:1560
	ds_read_b32 v15, v5 offset:1820
	s_lshl_b32 s4, s16, 17
	s_lshl_b32 s5, s17, 7
	s_add_u32 s4, s4, s5
	s_add_u32 s12, s12, s4
	s_addc_u32 s13, s13, 0
	v_lshl_add_u32 v7, v3, 11, v4
	s_waitcnt lgkmcnt(0)
	v_cvt_pk_bf16_f32 v224, v8, v9
	v_cvt_pk_bf16_f32 v225, v10, v11
	v_cvt_pk_bf16_f32 v226, v12, v13
	v_cvt_pk_bf16_f32 v227, v14, v15
	global_store_dwordx4 v7, v[224:227], s[12:13]
	s_branch .Lxp_next6

.Lxp_next6:
	s_load_dwordx2 s[12:13], s[0:1], 0xd8
	s_load_dwordx2 s[14:15], s[0:1], 0x38
	s_sub_u32 s2, s28, 160
	s_and_b32 s2, s2, 255
	s_cmp_lt_u32 s2, 96
	s_cselect_b32 s3, 1, 0
	s_cselect_b32 s2, s2, 0
	s_lshr_b32 s16, s2, 2
	s_and_b32 s17, s2, 3
	s_waitcnt vmcnt(63) lgkmcnt(0)
	s_cmp_eq_u32 s3, 0
	s_cbranch_scc1 .Lxp_idle7
	s_lshl_b32 s4, s17, 6
	s_add_u32 s4, s4, s29
	s_lshl_b32 s4, s4, 2
	s_add_u32 s4, s4, 1024
	s_add_u32 s14, s14, s4
	s_addc_u32 s15, s15, 0
	global_load_dword v216, v6, s[14:15] offset:0
	global_load_dword v217, v6, s[14:15] offset:32
	global_load_dword v218, v6, s[14:15] offset:64
	global_load_dword v219, v6, s[14:15] offset:96
	global_load_dword v220, v6, s[14:15] offset:128
	global_load_dword v221, v6, s[14:15] offset:160
	global_load_dword v222, v6, s[14:15] offset:192
	global_load_dword v223, v6, s[14:15] offset:224
	s_waitcnt vmcnt(0)
	v_mul_f32_e32 v72, v72, v216
	v_mul_f32_e32 v73, v73, v217
	v_mul_f32_e32 v74, v74, v218
	v_mul_f32_e32 v75, v75, v219
	v_mul_f32_e32 v76, v76, v220
	v_mul_f32_e32 v77, v77, v221
	v_mul_f32_e32 v78, v78, v222
	v_mul_f32_e32 v79, v79, v223
	ds_write_b32 v2, v72 offset:16640
	ds_write_b32 v2, v73 offset:18720
	ds_write_b32 v2, v74 offset:20800
	ds_write_b32 v2, v75 offset:22880
	ds_write_b32 v2, v76 offset:24960
	ds_write_b32 v2, v77 offset:27040
	ds_write_b32 v2, v78 offset:29120
	ds_write_b32 v2, v79 offset:31200
	s_waitcnt lgkmcnt(0)
	s_barrier
	ds_read_b32 v8, v5 offset:16640
	ds_read_b32 v9, v5 offset:16900
	ds_read_b32 v10, v5 offset:17160
	ds_read_b32 v11, v5 offset:17420
	ds_read_b32 v12, v5 offset:17680
	ds_read_b32 v13, v5 offset:17940
	ds_read_b32 v14, v5 offset:18200
	ds_read_b32 v15, v5 offset:18460
	s_lshl_b32 s4, s16, 15
	s_lshl_b32 s5, s17, 7
	s_add_u32 s4, s4, s5
	s_add_u32 s12, s12, s4
	s_addc_u32 s13, s13, 0
	v_lshl_add_u32 v7, v3, 9, v4
	s_waitcnt lgkmcnt(0)
	v_cvt_pk_bf16_f32 v224, v8, v9
	v_cvt_pk_bf16_f32 v225, v10, v11
	v_cvt_pk_bf16_f32 v226, v12, v13
	v_cvt_pk_bf16_f32 v227, v14, v15
	global_store_dwordx4 v7, v[224:227], s[12:13]
	s_branch .Lxp_next7

.Lxp_next7:
	s_load_dwordx2 s[12:13], s[0:1], 0xe8
	s_load_dwordx2 s[14:15], s[0:1], 0x40
	s_sub_u32 s2, s28, 0
	s_and_b32 s2, s2, 255
	s_cmp_lt_u32 s2, 64
	s_cselect_b32 s3, 1, 0
	s_cselect_b32 s2, s2, 0
	s_lshr_b32 s16, s2, 1
	s_and_b32 s17, s2, 1
	s_waitcnt vmcnt(63) lgkmcnt(0)
	s_cmp_eq_u32 s3, 0
	s_cbranch_scc1 .Lxp_idle8
	s_lshl_b32 s4, s17, 6
	s_add_u32 s4, s4, s29
	s_lshl_b32 s4, s4, 2
	s_add_u32 s4, s4, 512
	s_add_u32 s14, s14, s4
	s_addc_u32 s15, s15, 0
	global_load_dword v216, v6, s[14:15] offset:0
	global_load_dword v217, v6, s[14:15] offset:32
	global_load_dword v218, v6, s[14:15] offset:64
	global_load_dword v219, v6, s[14:15] offset:96
	global_load_dword v220, v6, s[14:15] offset:128
	global_load_dword v221, v6, s[14:15] offset:160
	global_load_dword v222, v6, s[14:15] offset:192
	global_load_dword v223, v6, s[14:15] offset:224
	s_waitcnt vmcnt(0)
	v_mul_f32_e32 v80, v80, v216
	v_mul_f32_e32 v81, v81, v217
	v_mul_f32_e32 v82, v82, v218
	v_mul_f32_e32 v83, v83, v219
	v_mul_f32_e32 v84, v84, v220
	v_mul_f32_e32 v85, v85, v221
	v_mul_f32_e32 v86, v86, v222
	v_mul_f32_e32 v87, v87, v223
	ds_write_b32 v2, v80 offset:0
	ds_write_b32 v2, v81 offset:2080
	ds_write_b32 v2, v82 offset:4160
	ds_write_b32 v2, v83 offset:6240
	ds_write_b32 v2, v84 offset:8320
	ds_write_b32 v2, v85 offset:10400
	ds_write_b32 v2, v86 offset:12480
	ds_write_b32 v2, v87 offset:14560
	s_waitcnt lgkmcnt(0)
	s_barrier
	ds_read_b32 v8, v5 offset:0
	ds_read_b32 v9, v5 offset:260
	ds_read_b32 v10, v5 offset:520
	ds_read_b32 v11, v5 offset:780
	ds_read_b32 v12, v5 offset:1040
	ds_read_b32 v13, v5 offset:1300
	ds_read_b32 v14, v5 offset:1560
	ds_read_b32 v15, v5 offset:1820
	s_lshl_b32 s4, s16, 14
	s_lshl_b32 s5, s17, 7
	s_add_u32 s4, s4, s5
	s_add_u32 s12, s12, s4
	s_addc_u32 s13, s13, 0
	v_lshl_add_u32 v7, v3, 8, v4
	s_waitcnt lgkmcnt(0)
	v_cvt_pk_bf16_f32 v224, v8, v9
	v_cvt_pk_bf16_f32 v225, v10, v11
	v_cvt_pk_bf16_f32 v226, v12, v13
	v_cvt_pk_bf16_f32 v227, v14, v15
	global_store_dwordx4 v7, v[224:227], s[12:13]
	s_branch .Lxp_next8

.Lxp_next8:
	s_load_dwordx2 s[12:13], s[0:1], 0xf8
	s_sub_u32 s2, s28, 64
	s_and_b32 s2, s2, 255
	s_cmp_lt_u32 s2, 256
	s_cselect_b32 s3, 1, 0
	s_cselect_b32 s2, s2, 0
	s_lshr_b32 s16, s2, 4
	s_and_b32 s17, s2, 15
	s_waitcnt vmcnt(63) lgkmcnt(0)
	s_cmp_eq_u32 s3, 0
	s_cbranch_scc1 .Lxp_idle9
	ds_write_b32 v2, v88 offset:16640
	ds_write_b32 v2, v89 offset:18720
	ds_write_b32 v2, v90 offset:20800
	ds_write_b32 v2, v91 offset:22880
	ds_write_b32 v2, v92 offset:24960
	ds_write_b32 v2, v93 offset:27040
	ds_write_b32 v2, v94 offset:29120
	ds_write_b32 v2, v95 offset:31200
	s_waitcnt lgkmcnt(0)
	s_barrier
	ds_read_b32 v8, v5 offset:16640
	ds_read_b32 v9, v5 offset:16900
	ds_read_b32 v10, v5 offset:17160
	ds_read_b32 v11, v5 offset:17420
	ds_read_b32 v12, v5 offset:17680
	ds_read_b32 v13, v5 offset:17940
	ds_read_b32 v14, v5 offset:18200
	ds_read_b32 v15, v5 offset:18460
	s_lshl_b32 s4, s16, 17
	s_lshl_b32 s5, s17, 7
	s_add_u32 s4, s4, s5
	s_add_u32 s12, s12, s4
	s_addc_u32 s13, s13, 0
	v_lshl_add_u32 v7, v3, 11, v4
	s_waitcnt lgkmcnt(0)
	v_cvt_pk_bf16_f32 v224, v8, v9
	v_cvt_pk_bf16_f32 v225, v10, v11
	v_cvt_pk_bf16_f32 v226, v12, v13
	v_cvt_pk_bf16_f32 v227, v14, v15
	global_store_dwordx4 v7, v[224:227], s[12:13]
	s_branch .Lxp_next9

.Lxp_next9:
	s_load_dwordx2 s[12:13], s[0:1], 0x100
	s_sub_u32 s2, s28, 64
	s_and_b32 s2, s2, 255
	s_cmp_lt_u32 s2, 576
	s_cselect_b32 s3, 1, 0
	s_cselect_b32 s2, s2, 0
	s_lshr_b32 s16, s2, 4
	s_and_b32 s17, s2, 15
	s_waitcnt vmcnt(63) lgkmcnt(0)
	s_cmp_eq_u32 s3, 0
	s_cbranch_scc1 .Lxp_idle10
	ds_write_b32 v2, v96 offset:0
	ds_write_b32 v2, v97 offset:2080
	ds_write_b32 v2, v98 offset:4160
	ds_write_b32 v2, v99 offset:6240
	ds_write_b32 v2, v100 offset:8320
	ds_write_b32 v2, v101 offset:10400
	ds_write_b32 v2, v102 offset:12480
	ds_write_b32 v2, v103 offset:14560
	s_waitcnt lgkmcnt(0)
	s_barrier
	ds_read_b32 v8, v5 offset:0
	ds_read_b32 v9, v5 offset:260
	ds_read_b32 v10, v5 offset:520
	ds_read_b32 v11, v5 offset:780
	ds_read_b32 v12, v5 offset:1040
	ds_read_b32 v13, v5 offset:1300
	ds_read_b32 v14, v5 offset:1560
	ds_read_b32 v15, v5 offset:1820
	s_lshl_b32 s4, s16, 17
	s_lshl_b32 s5, s17, 7
	s_add_u32 s4, s4, s5
	s_add_u32 s12, s12, s4
	s_addc_u32 s13, s13, 0
	v_lshl_add_u32 v7, v3, 11, v4
	s_waitcnt lgkmcnt(0)
	v_cvt_pk_bf16_f32 v224, v8, v9
	v_cvt_pk_bf16_f32 v225, v10, v11
	v_cvt_pk_bf16_f32 v226, v12, v13
	v_cvt_pk_bf16_f32 v227, v14, v15
	global_store_dwordx4 v7, v[224:227], s[12:13]
	s_branch .Lxp_next10

.Lxp_next10:
	s_load_dwordx2 s[12:13], s[0:1], 0x100
	s_sub_u32 s2, s28, 64
	s_and_b32 s2, s2, 255
	s_add_u32 s2, s2, 256
	s_cmp_lt_u32 s2, 576
	s_cselect_b32 s3, 1, 0
	s_cselect_b32 s2, s2, 0
	s_lshr_b32 s16, s2, 4
	s_and_b32 s17, s2, 15
	s_waitcnt vmcnt(63) lgkmcnt(0)
	s_cmp_eq_u32 s3, 0
	s_cbranch_scc1 .Lxp_idle11
	ds_write_b32 v2, v104 offset:16640
	ds_write_b32 v2, v105 offset:18720
	ds_write_b32 v2, v106 offset:20800
	ds_write_b32 v2, v107 offset:22880
	ds_write_b32 v2, v108 offset:24960
	ds_write_b32 v2, v109 offset:27040
	ds_write_b32 v2, v110 offset:29120
	ds_write_b32 v2, v111 offset:31200
	s_waitcnt lgkmcnt(0)
	s_barrier
	ds_read_b32 v8, v5 offset:16640
	ds_read_b32 v9, v5 offset:16900
	ds_read_b32 v10, v5 offset:17160
	ds_read_b32 v11, v5 offset:17420
	ds_read_b32 v12, v5 offset:17680
	ds_read_b32 v13, v5 offset:17940
	ds_read_b32 v14, v5 offset:18200
	ds_read_b32 v15, v5 offset:18460
	s_lshl_b32 s4, s16, 17
	s_lshl_b32 s5, s17, 7
	s_add_u32 s4, s4, s5
	s_add_u32 s12, s12, s4
	s_addc_u32 s13, s13, 0
	v_lshl_add_u32 v7, v3, 11, v4
	s_waitcnt lgkmcnt(0)
	v_cvt_pk_bf16_f32 v224, v8, v9
	v_cvt_pk_bf16_f32 v225, v10, v11
	v_cvt_pk_bf16_f32 v226, v12, v13
	v_cvt_pk_bf16_f32 v227, v14, v15
	global_store_dwordx4 v7, v[224:227], s[12:13]
	s_branch .Lxp_next11

.Lxp_next11:
	s_load_dwordx2 s[12:13], s[0:1], 0x100
	s_sub_u32 s2, s28, 64
	s_and_b32 s2, s2, 255
	s_add_u32 s2, s2, 512
	s_cmp_lt_u32 s2, 576
	s_cselect_b32 s3, 1, 0
	s_cselect_b32 s2, s2, 0
	s_lshr_b32 s16, s2, 4
	s_and_b32 s17, s2, 15
	s_waitcnt vmcnt(63) lgkmcnt(0)
	s_cmp_eq_u32 s3, 0
	s_cbranch_scc1 .Lxp_idle12
	ds_write_b32 v2, v112 offset:0
	ds_write_b32 v2, v113 offset:2080
	ds_write_b32 v2, v114 offset:4160
	ds_write_b32 v2, v115 offset:6240
	ds_write_b32 v2, v116 offset:8320
	ds_write_b32 v2, v117 offset:10400
	ds_write_b32 v2, v118 offset:12480
	ds_write_b32 v2, v119 offset:14560
	s_waitcnt lgkmcnt(0)
	s_barrier
	ds_read_b32 v8, v5 offset:0
	ds_read_b32 v9, v5 offset:260
	ds_read_b32 v10, v5 offset:520
	ds_read_b32 v11, v5 offset:780
	ds_read_b32 v12, v5 offset:1040
	ds_read_b32 v13, v5 offset:1300
	ds_read_b32 v14, v5 offset:1560
	ds_read_b32 v15, v5 offset:1820
	s_lshl_b32 s4, s16, 17
	s_lshl_b32 s5, s17, 7
	s_add_u32 s4, s4, s5
	s_add_u32 s12, s12, s4
	s_addc_u32 s13, s13, 0
	v_lshl_add_u32 v7, v3, 11, v4
	s_waitcnt lgkmcnt(0)
	v_cvt_pk_bf16_f32 v224, v8, v9
	v_cvt_pk_bf16_f32 v225, v10, v11
	v_cvt_pk_bf16_f32 v226, v12, v13
	v_cvt_pk_bf16_f32 v227, v14, v15
	global_store_dwordx4 v7, v[224:227], s[12:13]
	s_branch .Lxp_next12

.Lxp_next12:
	s_load_dwordx2 s[12:13], s[0:1], 0x108
	s_sub_u32 s2, s28, 128
	s_and_b32 s2, s2, 255
	s_cmp_lt_u32 s2, 256
	s_cselect_b32 s3, 1, 0
	s_cselect_b32 s2, s2, 0
	s_lshr_b32 s16, s2, 4
	s_and_b32 s17, s2, 15
	s_waitcnt vmcnt(63) lgkmcnt(0)
	s_cmp_eq_u32 s3, 0
	s_cbranch_scc1 .Lxp_idle13
	ds_write_b32 v2, v120 offset:16640
	ds_write_b32 v2, v121 offset:18720
	ds_write_b32 v2, v122 offset:20800
	ds_write_b32 v2, v123 offset:22880
	ds_write_b32 v2, v124 offset:24960
	ds_write_b32 v2, v125 offset:27040
	ds_write_b32 v2, v126 offset:29120
	ds_write_b32 v2, v127 offset:31200
	s_waitcnt lgkmcnt(0)
	s_barrier
	ds_read_b32 v8, v5 offset:16640
	ds_read_b32 v9, v5 offset:16900
	ds_read_b32 v10, v5 offset:17160
	ds_read_b32 v11, v5 offset:17420
	ds_read_b32 v12, v5 offset:17680
	ds_read_b32 v13, v5 offset:17940
	ds_read_b32 v14, v5 offset:18200
	ds_read_b32 v15, v5 offset:18460
	s_lshl_b32 s4, s16, 17
	s_lshl_b32 s5, s17, 7
	s_add_u32 s4, s4, s5
	s_add_u32 s12, s12, s4
	s_addc_u32 s13, s13, 0
	v_lshl_add_u32 v7, v3, 11, v4
	s_waitcnt lgkmcnt(0)
	v_cvt_pk_bf16_f32 v224, v8, v9
	v_cvt_pk_bf16_f32 v225, v10, v11
	v_cvt_pk_bf16_f32 v226, v12, v13
	v_cvt_pk_bf16_f32 v227, v14, v15
	global_store_dwordx4 v7, v[224:227], s[12:13]
	s_branch .Lxp_next13

.Lxp_next13:
	s_load_dwordx2 s[12:13], s[0:1], 0x110
	s_sub_u32 s2, s28, 128
	s_and_b32 s2, s2, 255
	s_cmp_lt_u32 s2, 960
	s_cselect_b32 s3, 1, 0
	s_cselect_b32 s2, s2, 0
	s_lshr_b32 s16, s2, 4
	s_and_b32 s17, s2, 15
	s_waitcnt vmcnt(63) lgkmcnt(0)
	s_cmp_eq_u32 s3, 0
	s_cbranch_scc1 .Lxp_idle14
	s_lshl_b32 s4, s16, 6
	s_sub_u32 s4, 3632, s4
	s_max_i32 s4, s4, 0
	v_cmp_gt_u32_e32 vcc, s4, v0
	v_cndmask_b32_e32 v128, 0, v128, vcc
	v_cndmask_b32_e32 v129, 0, v129, vcc
	v_cndmask_b32_e32 v130, 0, v130, vcc
	v_cndmask_b32_e32 v131, 0, v131, vcc
	v_cndmask_b32_e32 v132, 0, v132, vcc
	v_cndmask_b32_e32 v133, 0, v133, vcc
	v_cndmask_b32_e32 v134, 0, v134, vcc
	v_cndmask_b32_e32 v135, 0, v135, vcc
	ds_write_b32 v2, v128 offset:0
	ds_write_b32 v2, v129 offset:2080
	ds_write_b32 v2, v130 offset:4160
	ds_write_b32 v2, v131 offset:6240
	ds_write_b32 v2, v132 offset:8320
	ds_write_b32 v2, v133 offset:10400
	ds_write_b32 v2, v134 offset:12480
	ds_write_b32 v2, v135 offset:14560
	s_waitcnt lgkmcnt(0)
	s_barrier
	ds_read_b32 v8, v5 offset:0
	ds_read_b32 v9, v5 offset:260
	ds_read_b32 v10, v5 offset:520
	ds_read_b32 v11, v5 offset:780
	ds_read_b32 v12, v5 offset:1040
	ds_read_b32 v13, v5 offset:1300
	ds_read_b32 v14, v5 offset:1560
	ds_read_b32 v15, v5 offset:1820
	s_lshl_b32 s4, s16, 17
	s_lshl_b32 s5, s17, 7
	s_add_u32 s4, s4, s5
	s_add_u32 s12, s12, s4
	s_addc_u32 s13, s13, 0
	v_lshl_add_u32 v7, v3, 11, v4
	s_waitcnt lgkmcnt(0)
	v_cvt_pk_bf16_f32 v224, v8, v9
	v_cvt_pk_bf16_f32 v225, v10, v11
	v_cvt_pk_bf16_f32 v226, v12, v13
	v_cvt_pk_bf16_f32 v227, v14, v15
	global_store_dwordx4 v7, v[224:227], s[12:13]
	s_branch .Lxp_next14

.Lxp_next14:
	s_load_dwordx2 s[12:13], s[0:1], 0x110
	s_sub_u32 s2, s28, 128
	s_and_b32 s2, s2, 255
	s_add_u32 s2, s2, 256
	s_cmp_lt_u32 s2, 960
	s_cselect_b32 s3, 1, 0
	s_cselect_b32 s2, s2, 0
	s_lshr_b32 s16, s2, 4
	s_and_b32 s17, s2, 15
	s_waitcnt vmcnt(56) lgkmcnt(0)
	s_cmp_eq_u32 s3, 0
	s_cbranch_scc1 .Lxp_idle15
	s_lshl_b32 s4, s16, 6
	s_sub_u32 s4, 3632, s4
	s_max_i32 s4, s4, 0
	v_cmp_gt_u32_e32 vcc, s4, v0
	v_cndmask_b32_e32 v136, 0, v136, vcc
	v_cndmask_b32_e32 v137, 0, v137, vcc
	v_cndmask_b32_e32 v138, 0, v138, vcc
	v_cndmask_b32_e32 v139, 0, v139, vcc
	v_cndmask_b32_e32 v140, 0, v140, vcc
	v_cndmask_b32_e32 v141, 0, v141, vcc
	v_cndmask_b32_e32 v142, 0, v142, vcc
	v_cndmask_b32_e32 v143, 0, v143, vcc
	ds_write_b32 v2, v136 offset:16640
	ds_write_b32 v2, v137 offset:18720
	ds_write_b32 v2, v138 offset:20800
	ds_write_b32 v2, v139 offset:22880
	ds_write_b32 v2, v140 offset:24960
	ds_write_b32 v2, v141 offset:27040
	ds_write_b32 v2, v142 offset:29120
	ds_write_b32 v2, v143 offset:31200
	s_waitcnt lgkmcnt(0)
	s_barrier
	ds_read_b32 v8, v5 offset:16640
	ds_read_b32 v9, v5 offset:16900
	ds_read_b32 v10, v5 offset:17160
	ds_read_b32 v11, v5 offset:17420
	ds_read_b32 v12, v5 offset:17680
	ds_read_b32 v13, v5 offset:17940
	ds_read_b32 v14, v5 offset:18200
	ds_read_b32 v15, v5 offset:18460
	s_lshl_b32 s4, s16, 17
	s_lshl_b32 s5, s17, 7
	s_add_u32 s4, s4, s5
	s_add_u32 s12, s12, s4
	s_addc_u32 s13, s13, 0
	v_lshl_add_u32 v7, v3, 11, v4
	s_waitcnt lgkmcnt(0)
	v_cvt_pk_bf16_f32 v224, v8, v9
	v_cvt_pk_bf16_f32 v225, v10, v11
	v_cvt_pk_bf16_f32 v226, v12, v13
	v_cvt_pk_bf16_f32 v227, v14, v15
	global_store_dwordx4 v7, v[224:227], s[12:13]
	s_branch .Lxp_next15

.Lxp_next15:
	s_load_dwordx2 s[12:13], s[0:1], 0x110
	s_sub_u32 s2, s28, 128
	s_and_b32 s2, s2, 255
	s_add_u32 s2, s2, 512
	s_cmp_lt_u32 s2, 960
	s_cselect_b32 s3, 1, 0
	s_cselect_b32 s2, s2, 0
	s_lshr_b32 s16, s2, 4
	s_and_b32 s17, s2, 15
	s_waitcnt vmcnt(48) lgkmcnt(0)
	s_cmp_eq_u32 s3, 0
	s_cbranch_scc1 .Lxp_idle16
	s_lshl_b32 s4, s16, 6
	s_sub_u32 s4, 3632, s4
	s_max_i32 s4, s4, 0
	v_cmp_gt_u32_e32 vcc, s4, v0
	v_cndmask_b32_e32 v144, 0, v144, vcc
	v_cndmask_b32_e32 v145, 0, v145, vcc
	v_cndmask_b32_e32 v146, 0, v146, vcc
	v_cndmask_b32_e32 v147, 0, v147, vcc
	v_cndmask_b32_e32 v148, 0, v148, vcc
	v_cndmask_b32_e32 v149, 0, v149, vcc
	v_cndmask_b32_e32 v150, 0, v150, vcc
	v_cndmask_b32_e32 v151, 0, v151, vcc
	ds_write_b32 v2, v144 offset:0
	ds_write_b32 v2, v145 offset:2080
	ds_write_b32 v2, v146 offset:4160
	ds_write_b32 v2, v147 offset:6240
	ds_write_b32 v2, v148 offset:8320
	ds_write_b32 v2, v149 offset:10400
	ds_write_b32 v2, v150 offset:12480
	ds_write_b32 v2, v151 offset:14560
	s_waitcnt lgkmcnt(0)
	s_barrier
	ds_read_b32 v8, v5 offset:0
	ds_read_b32 v9, v5 offset:260
	ds_read_b32 v10, v5 offset:520
	ds_read_b32 v11, v5 offset:780
	ds_read_b32 v12, v5 offset:1040
	ds_read_b32 v13, v5 offset:1300
	ds_read_b32 v14, v5 offset:1560
	ds_read_b32 v15, v5 offset:1820
	s_lshl_b32 s4, s16, 17
	s_lshl_b32 s5, s17, 7
	s_add_u32 s4, s4, s5
	s_add_u32 s12, s12, s4
	s_addc_u32 s13, s13, 0
	v_lshl_add_u32 v7, v3, 11, v4
	s_waitcnt lgkmcnt(0)
	v_cvt_pk_bf16_f32 v224, v8, v9
	v_cvt_pk_bf16_f32 v225, v10, v11
	v_cvt_pk_bf16_f32 v226, v12, v13
	v_cvt_pk_bf16_f32 v227, v14, v15
	global_store_dwordx4 v7, v[224:227], s[12:13]
	s_branch .Lxp_next16

.Lxp_next16:
	s_load_dwordx2 s[12:13], s[0:1], 0x110
	s_sub_u32 s2, s28, 128
	s_and_b32 s2, s2, 255
	s_add_u32 s2, s2, 768
	s_cmp_lt_u32 s2, 960
	s_cselect_b32 s3, 1, 0
	s_cselect_b32 s2, s2, 0
	s_lshr_b32 s16, s2, 4
	s_and_b32 s17, s2, 15
	s_waitcnt vmcnt(40) lgkmcnt(0)
	s_cmp_eq_u32 s3, 0
	s_cbranch_scc1 .Lxp_idle17
	s_lshl_b32 s4, s16, 6
	s_sub_u32 s4, 3632, s4
	s_max_i32 s4, s4, 0
	v_cmp_gt_u32_e32 vcc, s4, v0
	v_cndmask_b32_e32 v152, 0, v152, vcc
	v_cndmask_b32_e32 v153, 0, v153, vcc
	v_cndmask_b32_e32 v154, 0, v154, vcc
	v_cndmask_b32_e32 v155, 0, v155, vcc
	v_cndmask_b32_e32 v156, 0, v156, vcc
	v_cndmask_b32_e32 v157, 0, v157, vcc
	v_cndmask_b32_e32 v158, 0, v158, vcc
	v_cndmask_b32_e32 v159, 0, v159, vcc
	ds_write_b32 v2, v152 offset:16640
	ds_write_b32 v2, v153 offset:18720
	ds_write_b32 v2, v154 offset:20800
	ds_write_b32 v2, v155 offset:22880
	ds_write_b32 v2, v156 offset:24960
	ds_write_b32 v2, v157 offset:27040
	ds_write_b32 v2, v158 offset:29120
	ds_write_b32 v2, v159 offset:31200
	s_waitcnt lgkmcnt(0)
	s_barrier
	ds_read_b32 v8, v5 offset:16640
	ds_read_b32 v9, v5 offset:16900
	ds_read_b32 v10, v5 offset:17160
	ds_read_b32 v11, v5 offset:17420
	ds_read_b32 v12, v5 offset:17680
	ds_read_b32 v13, v5 offset:17940
	ds_read_b32 v14, v5 offset:18200
	ds_read_b32 v15, v5 offset:18460
	s_lshl_b32 s4, s16, 17
	s_lshl_b32 s5, s17, 7
	s_add_u32 s4, s4, s5
	s_add_u32 s12, s12, s4
	s_addc_u32 s13, s13, 0
	v_lshl_add_u32 v7, v3, 11, v4
	s_waitcnt lgkmcnt(0)
	v_cvt_pk_bf16_f32 v224, v8, v9
	v_cvt_pk_bf16_f32 v225, v10, v11
	v_cvt_pk_bf16_f32 v226, v12, v13
	v_cvt_pk_bf16_f32 v227, v14, v15
	global_store_dwordx4 v7, v[224:227], s[12:13]
	s_branch .Lxp_next17

.Lxp_next17:
	s_load_dwordx2 s[12:13], s[0:1], 0x118
	s_sub_u32 s2, s28, 64
	s_and_b32 s2, s2, 255
	s_cmp_lt_u32 s2, 128
	s_cselect_b32 s3, 1, 0
	s_cselect_b32 s2, s2, 0
	s_lshr_b32 s16, s2, 5
	s_and_b32 s17, s2, 31
	s_waitcnt vmcnt(32) lgkmcnt(0)
	s_cmp_eq_u32 s3, 0
	s_cbranch_scc1 .Lxp_idle18
	s_lshl_b32 s4, s16, 6
	s_sub_u32 s4, 128, s4
	s_max_i32 s4, s4, 0
	v_cmp_gt_u32_e32 vcc, s4, v0
	v_cndmask_b32_e32 v160, 0, v160, vcc
	v_cndmask_b32_e32 v161, 0, v161, vcc
	v_cndmask_b32_e32 v162, 0, v162, vcc
	v_cndmask_b32_e32 v163, 0, v163, vcc
	v_cndmask_b32_e32 v164, 0, v164, vcc
	v_cndmask_b32_e32 v165, 0, v165, vcc
	v_cndmask_b32_e32 v166, 0, v166, vcc
	v_cndmask_b32_e32 v167, 0, v167, vcc
	ds_write_b32 v2, v160 offset:0
	ds_write_b32 v2, v161 offset:2080
	ds_write_b32 v2, v162 offset:4160
	ds_write_b32 v2, v163 offset:6240
	ds_write_b32 v2, v164 offset:8320
	ds_write_b32 v2, v165 offset:10400
	ds_write_b32 v2, v166 offset:12480
	ds_write_b32 v2, v167 offset:14560
	s_waitcnt lgkmcnt(0)
	s_barrier
	ds_read_b32 v8, v5 offset:0
	ds_read_b32 v9, v5 offset:260
	ds_read_b32 v10, v5 offset:520
	ds_read_b32 v11, v5 offset:780
	ds_read_b32 v12, v5 offset:1040
	ds_read_b32 v13, v5 offset:1300
	ds_read_b32 v14, v5 offset:1560
	ds_read_b32 v15, v5 offset:1820
	s_lshl_b32 s4, s16, 18
	s_lshl_b32 s5, s17, 7
	s_add_u32 s4, s4, s5
	s_add_u32 s12, s12, s4
	s_addc_u32 s13, s13, 0
	v_lshl_add_u32 v7, v3, 12, v4
	s_waitcnt lgkmcnt(0)
	v_cvt_pk_bf16_f32 v224, v8, v9
	v_cvt_pk_bf16_f32 v225, v10, v11
	v_cvt_pk_bf16_f32 v226, v12, v13
	v_cvt_pk_bf16_f32 v227, v14, v15
	global_store_dwordx4 v7, v[224:227], s[12:13]
	s_branch .Lxp_next18

.Lxp_next18:
	s_load_dwordx2 s[12:13], s[0:1], 0x120
	s_sub_u32 s2, s28, 192
	s_and_b32 s2, s2, 255
	s_cmp_lt_u32 s2, 8
	s_cselect_b32 s3, 1, 0
	s_cselect_b32 s2, s2, 0
	s_lshr_b32 s16, s2, 1
	s_and_b32 s17, s2, 1
	s_waitcnt vmcnt(24) lgkmcnt(0)
	s_cmp_eq_u32 s3, 0
	s_cbranch_scc1 .Lxp_idle19
	s_lshl_b32 s4, s16, 6
	s_sub_u32 s4, 64, s4
	s_max_i32 s4, s4, 0
	v_cmp_gt_u32_e32 vcc, s4, v0
	v_cndmask_b32_e32 v168, 0, v168, vcc
	v_cndmask_b32_e32 v169, 0, v169, vcc
	v_cndmask_b32_e32 v170, 0, v170, vcc
	v_cndmask_b32_e32 v171, 0, v171, vcc
	v_cndmask_b32_e32 v172, 0, v172, vcc
	v_cndmask_b32_e32 v173, 0, v173, vcc
	v_cndmask_b32_e32 v174, 0, v174, vcc
	v_cndmask_b32_e32 v175, 0, v175, vcc
	ds_write_b32 v2, v168 offset:16640
	ds_write_b32 v2, v169 offset:18720
	ds_write_b32 v2, v170 offset:20800
	ds_write_b32 v2, v171 offset:22880
	ds_write_b32 v2, v172 offset:24960
	ds_write_b32 v2, v173 offset:27040
	ds_write_b32 v2, v174 offset:29120
	ds_write_b32 v2, v175 offset:31200
	s_waitcnt lgkmcnt(0)
	s_barrier
	ds_read_b32 v8, v5 offset:16640
	ds_read_b32 v9, v5 offset:16900
	ds_read_b32 v10, v5 offset:17160
	ds_read_b32 v11, v5 offset:17420
	ds_read_b32 v12, v5 offset:17680
	ds_read_b32 v13, v5 offset:17940
	ds_read_b32 v14, v5 offset:18200
	ds_read_b32 v15, v5 offset:18460
	s_lshl_b32 s4, s16, 14
	s_lshl_b32 s5, s17, 7
	s_add_u32 s4, s4, s5
	s_add_u32 s12, s12, s4
	s_addc_u32 s13, s13, 0
	v_lshl_add_u32 v7, v3, 8, v4
	s_waitcnt lgkmcnt(0)
	v_cvt_pk_bf16_f32 v224, v8, v9
	v_cvt_pk_bf16_f32 v225, v10, v11
	v_cvt_pk_bf16_f32 v226, v12, v13
	v_cvt_pk_bf16_f32 v227, v14, v15
	global_store_dwordx4 v7, v[224:227], s[12:13]
	s_branch .Lxp_next19

.Lxp_next19:
	s_load_dwordx2 s[12:13], s[0:1], 0x128
	s_sub_u32 s2, s28, 200
	s_and_b32 s2, s2, 255
	s_cmp_lt_u32 s2, 128
	s_cselect_b32 s3, 1, 0
	s_cselect_b32 s2, s2, 0
	s_lshr_b32 s16, s2, 5
	s_and_b32 s17, s2, 31
	s_waitcnt vmcnt(16) lgkmcnt(0)
	s_cmp_eq_u32 s3, 0
	s_cbranch_scc1 .Lxp_idle20
	s_lshl_b32 s4, s16, 6
	s_sub_u32 s4, 128, s4
	s_max_i32 s4, s4, 0
	v_cmp_gt_u32_e32 vcc, s4, v0
	v_cndmask_b32_e32 v176, 0, v176, vcc
	v_cndmask_b32_e32 v177, 0, v177, vcc
	v_cndmask_b32_e32 v178, 0, v178, vcc
	v_cndmask_b32_e32 v179, 0, v179, vcc
	v_cndmask_b32_e32 v180, 0, v180, vcc
	v_cndmask_b32_e32 v181, 0, v181, vcc
	v_cndmask_b32_e32 v182, 0, v182, vcc
	v_cndmask_b32_e32 v183, 0, v183, vcc
	ds_write_b32 v2, v176 offset:0
	ds_write_b32 v2, v177 offset:2080
	ds_write_b32 v2, v178 offset:4160
	ds_write_b32 v2, v179 offset:6240
	ds_write_b32 v2, v180 offset:8320
	ds_write_b32 v2, v181 offset:10400
	ds_write_b32 v2, v182 offset:12480
	ds_write_b32 v2, v183 offset:14560
	s_waitcnt lgkmcnt(0)
	s_barrier
	ds_read_b32 v8, v5 offset:0
	ds_read_b32 v9, v5 offset:260
	ds_read_b32 v10, v5 offset:520
	ds_read_b32 v11, v5 offset:780
	ds_read_b32 v12, v5 offset:1040
	ds_read_b32 v13, v5 offset:1300
	ds_read_b32 v14, v5 offset:1560
	ds_read_b32 v15, v5 offset:1820
	s_lshl_b32 s4, s16, 18
	s_lshl_b32 s5, s17, 7
	s_add_u32 s4, s4, s5
	s_add_u32 s12, s12, s4
	s_addc_u32 s13, s13, 0
	v_lshl_add_u32 v7, v3, 12, v4
	s_waitcnt lgkmcnt(0)
	v_cvt_pk_bf16_f32 v224, v8, v9
	v_cvt_pk_bf16_f32 v225, v10, v11
	v_cvt_pk_bf16_f32 v226, v12, v13
	v_cvt_pk_bf16_f32 v227, v14, v15
	global_store_dwordx4 v7, v[224:227], s[12:13]
	s_branch .Lxp_next20

.Lxp_next20:
	s_load_dwordx2 s[12:13], s[0:1], 0x130
	s_sub_u32 s2, s28, 72
	s_and_b32 s2, s2, 255
	s_cmp_lt_u32 s2, 8
	s_cselect_b32 s3, 1, 0
	s_cselect_b32 s2, s2, 0
	s_lshr_b32 s16, s2, 1
	s_and_b32 s17, s2, 1
	s_waitcnt vmcnt(8) lgkmcnt(0)
	s_cmp_eq_u32 s3, 0
	s_cbranch_scc1 .Lxp_idle21
	s_lshl_b32 s4, s16, 6
	s_sub_u32 s4, 64, s4
	s_max_i32 s4, s4, 0
	v_cmp_gt_u32_e32 vcc, s4, v0
	v_cndmask_b32_e32 v184, 0, v184, vcc
	v_cndmask_b32_e32 v185, 0, v185, vcc
	v_cndmask_b32_e32 v186, 0, v186, vcc
	v_cndmask_b32_e32 v187, 0, v187, vcc
	v_cndmask_b32_e32 v188, 0, v188, vcc
	v_cndmask_b32_e32 v189, 0, v189, vcc
	v_cndmask_b32_e32 v190, 0, v190, vcc
	v_cndmask_b32_e32 v191, 0, v191, vcc
	ds_write_b32 v2, v184 offset:16640
	ds_write_b32 v2, v185 offset:18720
	ds_write_b32 v2, v186 offset:20800
	ds_write_b32 v2, v187 offset:22880
	ds_write_b32 v2, v188 offset:24960
	ds_write_b32 v2, v189 offset:27040
	ds_write_b32 v2, v190 offset:29120
	ds_write_b32 v2, v191 offset:31200
	s_waitcnt lgkmcnt(0)
	s_barrier
	ds_read_b32 v8, v5 offset:16640
	ds_read_b32 v9, v5 offset:16900
	ds_read_b32 v10, v5 offset:17160
	ds_read_b32 v11, v5 offset:17420
	ds_read_b32 v12, v5 offset:17680
	ds_read_b32 v13, v5 offset:17940
	ds_read_b32 v14, v5 offset:18200
	ds_read_b32 v15, v5 offset:18460
	s_lshl_b32 s4, s16, 14
	s_lshl_b32 s5, s17, 7
	s_add_u32 s4, s4, s5
	s_add_u32 s12, s12, s4
	s_addc_u32 s13, s13, 0
	v_lshl_add_u32 v7, v3, 8, v4
	s_waitcnt lgkmcnt(0)
	v_cvt_pk_bf16_f32 v224, v8, v9
	v_cvt_pk_bf16_f32 v225, v10, v11
	v_cvt_pk_bf16_f32 v226, v12, v13
	v_cvt_pk_bf16_f32 v227, v14, v15
	global_store_dwordx4 v7, v[224:227], s[12:13]
	s_branch .Lxp_next21

.Lxp_next21:
	s_load_dwordx2 s[12:13], s[0:1], 0x138
	s_sub_u32 s2, s28, 80
	s_and_b32 s2, s2, 255
	s_cmp_lt_u32 s2, 256
	s_cselect_b32 s3, 1, 0
	s_cselect_b32 s2, s2, 0
	s_lshr_b32 s16, s2, 4
	s_and_b32 s17, s2, 15
	s_waitcnt vmcnt(0) lgkmcnt(0)
	s_cmp_eq_u32 s3, 0
	s_cbranch_scc1 .Lxp_idle22
	ds_write_b32 v2, v192 offset:0
	ds_write_b32 v2, v193 offset:2080
	ds_write_b32 v2, v194 offset:4160
	ds_write_b32 v2, v195 offset:6240
	ds_write_b32 v2, v196 offset:8320
	ds_write_b32 v2, v197 offset:10400
	ds_write_b32 v2, v198 offset:12480
	ds_write_b32 v2, v199 offset:14560
	s_waitcnt lgkmcnt(0)
	s_barrier
	ds_read_b32 v8, v5 offset:0
	ds_read_b32 v9, v5 offset:260
	ds_read_b32 v10, v5 offset:520
	ds_read_b32 v11, v5 offset:780
	ds_read_b32 v12, v5 offset:1040
	ds_read_b32 v13, v5 offset:1300
	ds_read_b32 v14, v5 offset:1560
	ds_read_b32 v15, v5 offset:1820
	s_lshl_b32 s4, s16, 17
	s_lshl_b32 s5, s17, 7
	s_add_u32 s4, s4, s5
	s_add_u32 s12, s12, s4
	s_addc_u32 s13, s13, 0
	v_lshl_add_u32 v7, v3, 11, v4
	s_waitcnt lgkmcnt(0)
	v_cvt_pk_bf16_f32 v224, v8, v9
	v_cvt_pk_bf16_f32 v225, v10, v11
	v_cvt_pk_bf16_f32 v226, v12, v13
	v_cvt_pk_bf16_f32 v227, v14, v15
	global_store_dwordx4 v7, v[224:227], s[12:13]
	s_branch .Lxp_next22

.Lxp_next22:
	s_waitcnt vmcnt(0)
